# GLA backward epilogue: batch p.of/gog loads and wave reductions; hyena finalize: 16 neighbour loads in flight
# speedup vs baseline: 1.0272x; 1.0272x over previous
; __device__ __forceinline__ float bf2f(bf16 b) { return __uint_as_float(((unsigned)b) << 16); }
; __device__ __forceinline__ void hy_fin_tile(const Params& p, int layer, int item, float* sT) {
;     ...
;   {
;     const int cl = tid >> 2, sg = tid & 3;
;     const u4v* s4 = (const u4v*)(p.uT + (size_t)(c0 + cl) * T_TOK + t0 + sg * 16);
;     u4v a = s4[0], b = s4[1];
;     unsigned u[8] = {a.x, a.y, a.z, a.w, b.x, b.y, b.z, b.w};
; #pragma unroll
;     for (int e = 0; e < 8; ++e) {
;       sT[cl * 65 + sg * 16 + 2 * e] = __uint_as_float(u[e] << 16);
;       sT[cl * 65 + sg * 16 + 2 * e + 1] = __uint_as_float(u[e] & 0xffff0000u);
;     }
;   }
;   __syncthreads();
;   {
;     const int cl = tid & 63, tq = tid >> 6;
;     const int c = c0 + cl;
;     const float w0 = cw[1024 + c], w1 = cw[1536 + 1024 + c], w2 = cw[3072 + 1024 + c], bb = cb[1024 + c];
;     const int ts = t0 + tq * 16;
;     const int L = tok_len(ts);
;     const int pos = tok_pos(ts);
;     const int tpv = pos > 0 ? ts - 1 : ts;
;     float xp = bf2f(p.hx2[(size_t)tpv * 512 + c]);
;     xp = pos > 0 ? xp : 0.f;
;     float xc = bf2f(p.hx2[(size_t)ts * 512 + c]);
; #pragma unroll
;     for (int j = 0; j < 16; ++j) {
;       const int t = ts + j;
;       const bool hn = (pos + j) < L - 1;
;       const int tn = hn ? t + 1 : t;
;       float xn = bf2f(p.hx2[(size_t)tn * 512 + c]);
;       xn = hn ? xn : 0.f;
;       float x2c = xp * w0 + xc * w1 + xn * w2 + bb;
;       p.hv[(size_t)t * 512 + c] = f2bf(x2c * sT[cl * 65 + tq * 16 + j]);
;       xp = xc; xc = xn;
;     }
.LBB0_1115:
	v_readlane_b32 s2, v255, 15
	s_lshl_b32 s0, s2, 3
	s_lshl_b32 s2, s2, 6
	v_mov_b32_e32 v10, v195
	s_and_b32 s2, s2, 0x1c0
	v_readlane_b32 s64, v254, 18
	v_ashrrev_i32_e32 v14, 2, v10
	v_add_u32_e32 v2, s2, v14
	v_ashrrev_i32_e32 v3, 31, v2
	s_and_b32 s0, s0, 0x7fffffc0
	v_lshlrev_b64 v[2:3], 16, v[2:3]
	v_readlane_b32 s74, v254, 28
	v_readlane_b32 s75, v254, 29
	v_lshlrev_b32_e32 v0, 4, v10
	s_addk_i32 s0, 0xa700
	v_lshl_add_u64 v[2:3], s[74:75], 0, v[2:3]
	v_and_b32_e32 v11, 48, v0
	v_lshl_add_u64 v[2:3], s[0:1], 1, v[2:3]
	v_lshlrev_b32_e32 v0, 1, v11
	v_lshl_add_u64 v[6:7], v[2:3], 0, v[0:1]
	global_load_dwordx4 v[2:5], v[6:7], off offset:16
	s_nop 0
	global_load_dwordx4 v[6:9], v[6:7], off
	s_movk_i32 s20, 0x104
	v_mul_lo_u32 v0, v14, s20
	v_lshl_add_u32 v0, v11, 2, v0
	v_and_b32_e32 v15, 63, v10
	v_readlane_b32 s22, v255, 5
	v_readlane_b32 s23, v255, 6
	v_and_b32_e32 v16, -16, v14
	v_readlane_b32 s76, v254, 30
	v_readlane_b32 s77, v254, 31
	v_readlane_b32 s78, v254, 32
	v_readlane_b32 s79, v254, 33
	v_readlane_b32 s76, v252, 23
	v_readlane_b32 s90, v252, 37
	v_readlane_b32 s91, v252, 38
	v_readlane_b32 s86, v252, 33
	v_readlane_b32 s87, v252, 34
	v_readlane_b32 s65, v254, 19
	v_readlane_b32 s66, v254, 20
	v_readlane_b32 s67, v254, 21
	v_readlane_b32 s68, v254, 22
	v_readlane_b32 s69, v254, 23
	v_readlane_b32 s70, v254, 24
	v_readlane_b32 s71, v254, 25
	v_readlane_b32 s72, v254, 26
	v_readlane_b32 s73, v254, 27
	v_readlane_b32 s77, v252, 24
	v_readlane_b32 s78, v252, 25
	v_readlane_b32 s79, v252, 26
	v_readlane_b32 s80, v252, 27
	v_readlane_b32 s81, v252, 28
	v_readlane_b32 s82, v252, 29
	v_readlane_b32 s83, v252, 30
	v_readlane_b32 s84, v252, 31
	v_readlane_b32 s85, v252, 32
	v_readlane_b32 s88, v252, 35
	v_readlane_b32 s89, v252, 36
	s_waitcnt vmcnt(0)
	v_lshlrev_b32_e32 v11, 16, v6
	v_and_b32_e32 v6, 0xffff0000, v6
	ds_write2_b32 v0, v11, v6 offset1:1
	v_lshlrev_b32_e32 v6, 16, v7
	v_and_b32_e32 v7, 0xffff0000, v7
	ds_write2_b32 v0, v6, v7 offset0:2 offset1:3
	v_lshlrev_b32_e32 v6, 16, v8
	v_and_b32_e32 v7, 0xffff0000, v8
	ds_write2_b32 v0, v6, v7 offset0:4 offset1:5
	v_lshlrev_b32_e32 v6, 16, v9
	v_and_b32_e32 v7, 0xffff0000, v9
	ds_write2_b32 v0, v6, v7 offset0:6 offset1:7
	v_lshlrev_b32_e32 v6, 16, v2
	v_and_b32_e32 v2, 0xffff0000, v2
	ds_write2_b32 v0, v6, v2 offset0:8 offset1:9
	v_lshlrev_b32_e32 v2, 16, v3
	v_and_b32_e32 v3, 0xffff0000, v3
	ds_write2_b32 v0, v2, v3 offset0:10 offset1:11
	v_lshlrev_b32_e32 v2, 16, v4
	v_and_b32_e32 v3, 0xffff0000, v4
	ds_write2_b32 v0, v2, v3 offset0:12 offset1:13
	v_lshlrev_b32_e32 v2, 16, v5
	v_and_b32_e32 v3, 0xffff0000, v5
	v_or_b32_e32 v6, s2, v15
	ds_write2_b32 v0, v2, v3 offset0:14 offset1:15
	v_lshlrev_b32_e32 v0, 2, v6
	v_readlane_b32 s2, v255, 3
	v_or_b32_e32 v7, 0x1000, v0
	v_readlane_b32 s3, v255, 4
	s_waitcnt lgkmcnt(0)
	s_barrier
	v_lshl_add_u64 v[2:3], s[2:3], 0, v[0:1]
	global_load_dword v13, v7, s[22:23]
	s_nop 0
	global_load_dword v10, v7, s[2:3]
	s_movk_i32 s2, 0x2000
	v_add_co_u32_e32 v4, vcc, s2, v2
	s_movk_i32 s2, 0x4000
	s_nop 0
	v_addc_co_u32_e32 v5, vcc, 0, v3, vcc
	v_add_co_u32_e32 v2, vcc, s2, v2
	global_load_dword v11, v[4:5], off offset:2048
	s_nop 0
	v_addc_co_u32_e32 v3, vcc, 0, v3, vcc
	global_load_dword v12, v[2:3], off
	v_add_u32_e32 v2, s0, v16
	v_cmp_gt_i32_e32 vcc, s2, v2
	v_and_b32_e32 v0, 0x7f0, v2
	s_nop 0
	v_cndmask_b32_e32 v14, v0, v2, vcc
	v_cmp_lt_i32_e64 s[2:3], 0, v14
	v_lshlrev_b32_e32 v0, 1, v6
	v_lshl_add_u64 v[6:7], s[90:91], 0, v[0:1]
	v_subbrev_co_u32_e64 v4, s[40:41], 0, v2, s[2:3]
	v_ashrrev_i32_e32 v5, 31, v4
	v_lshlrev_b64 v[4:5], 10, v[4:5]
	v_lshl_add_u64 v[4:5], s[90:91], 0, v[4:5]
	v_lshl_add_u64 v[4:5], v[4:5], 0, v[0:1]
	global_load_ushort v3, v[4:5], off
	s_waitcnt vmcnt(0)
	v_lshlrev_b32_e32 v3, 16, v3
	v_cndmask_b32_e64 v18, 0, v3, s[2:3]
	v_ashrrev_i32_e32 v3, 31, v2
	v_lshlrev_b64 v[8:9], 10, v[2:3]
	v_lshl_add_u64 v[4:5], s[90:91], 0, v[8:9]
	v_lshl_add_u64 v[4:5], v[4:5], 0, v[0:1]
	global_load_ushort v3, v[4:5], off
	v_lshlrev_b32_e32 v4, 2, v16
	v_mad_u32_u24 v15, v15, s20, v4
	v_lshl_add_u64 v[4:5], s[86:87], 0, v[0:1]
	v_lshl_add_u64 v[8:9], v[4:5], 0, v[8:9]
	s_mov_b64 s[20:21], 0
	s_waitcnt vmcnt(0)
	v_lshlrev_b32_e32 v20, 16, v3
	v_cndmask_b32_e32 v3, v225, v226, vcc
	v_cmp_lt_i32_e32 vcc, v14, v3
	s_nop 1
	v_addc_co_u32_e64 v24, s[2:3], 0, v2, vcc
	v_ashrrev_i32_e32 v25, 31, v24
	v_lshlrev_b64 v[24:25], 10, v[24:25]
	v_lshl_add_u64 v[24:25], v[6:7], 0, v[24:25]
	global_load_ushort v40, v[24:25], off
	v_add_u32_e32 v26, 1, v14
	v_cmp_lt_i32_e32 vcc, v26, v3
	s_nop 1
	v_addc_co_u32_e64 v24, s[2:3], 1, v2, vcc
	v_ashrrev_i32_e32 v25, 31, v24
	v_lshlrev_b64 v[24:25], 10, v[24:25]
	v_lshl_add_u64 v[24:25], v[6:7], 0, v[24:25]
	global_load_ushort v41, v[24:25], off
	v_add_u32_e32 v26, 2, v14
	v_cmp_lt_i32_e32 vcc, v26, v3
	s_nop 1
	v_addc_co_u32_e64 v24, s[2:3], 2, v2, vcc
	v_ashrrev_i32_e32 v25, 31, v24
	v_lshlrev_b64 v[24:25], 10, v[24:25]
	v_lshl_add_u64 v[24:25], v[6:7], 0, v[24:25]
	global_load_ushort v42, v[24:25], off
	v_add_u32_e32 v26, 3, v14
	v_cmp_lt_i32_e32 vcc, v26, v3
	s_nop 1
	v_addc_co_u32_e64 v24, s[2:3], 3, v2, vcc
	v_ashrrev_i32_e32 v25, 31, v24
	v_lshlrev_b64 v[24:25], 10, v[24:25]
	v_lshl_add_u64 v[24:25], v[6:7], 0, v[24:25]
	global_load_ushort v43, v[24:25], off
	v_add_u32_e32 v26, 4, v14
	v_cmp_lt_i32_e32 vcc, v26, v3
	s_nop 1
	v_addc_co_u32_e64 v24, s[2:3], 4, v2, vcc
	v_ashrrev_i32_e32 v25, 31, v24
	v_lshlrev_b64 v[24:25], 10, v[24:25]
	v_lshl_add_u64 v[24:25], v[6:7], 0, v[24:25]
	global_load_ushort v44, v[24:25], off
	v_add_u32_e32 v26, 5, v14
	v_cmp_lt_i32_e32 vcc, v26, v3
	s_nop 1
; __device__ __forceinline__ float bf2f(bf16 b) { return __uint_as_float(((unsigned)b) << 16); }
; __device__ __forceinline__ void hy_fin_tile(const Params& p, int layer, int item, float* sT) {
;     ...
;     for (int j = 0; j < 16; ++j) {
;       const int t = ts + j;
;       const bool hn = (pos + j) < L - 1;
;       const int tn = hn ? t + 1 : t;
;       float xn = bf2f(p.hx2[(size_t)tn * 512 + c]);
;       xn = hn ? xn : 0.f;
;       float x2c = xp * w0 + xc * w1 + xn * w2 + bb;
;       p.hv[(size_t)t * 512 + c] = f2bf(x2c * sT[cl * 65 + tq * 16 + j]);
;       xp = xc; xc = xn;
;     }
	v_addc_co_u32_e64 v24, s[2:3], 5, v2, vcc
	v_ashrrev_i32_e32 v25, 31, v24
	v_lshlrev_b64 v[24:25], 10, v[24:25]
	v_lshl_add_u64 v[24:25], v[6:7], 0, v[24:25]
	global_load_ushort v45, v[24:25], off
	v_add_u32_e32 v26, 6, v14
	v_cmp_lt_i32_e32 vcc, v26, v3
	s_nop 1
	v_addc_co_u32_e64 v24, s[2:3], 6, v2, vcc
	v_ashrrev_i32_e32 v25, 31, v24
	v_lshlrev_b64 v[24:25], 10, v[24:25]
	v_lshl_add_u64 v[24:25], v[6:7], 0, v[24:25]
	global_load_ushort v46, v[24:25], off
	v_add_u32_e32 v26, 7, v14
	v_cmp_lt_i32_e32 vcc, v26, v3
	s_nop 1
	v_addc_co_u32_e64 v24, s[2:3], 7, v2, vcc
	v_ashrrev_i32_e32 v25, 31, v24
	v_lshlrev_b64 v[24:25], 10, v[24:25]
	v_lshl_add_u64 v[24:25], v[6:7], 0, v[24:25]
	global_load_ushort v47, v[24:25], off
	v_add_u32_e32 v26, 8, v14
	v_cmp_lt_i32_e32 vcc, v26, v3
	s_nop 1
	v_addc_co_u32_e64 v24, s[2:3], 8, v2, vcc
	v_ashrrev_i32_e32 v25, 31, v24
	v_lshlrev_b64 v[24:25], 10, v[24:25]
	v_lshl_add_u64 v[24:25], v[6:7], 0, v[24:25]
	global_load_ushort v48, v[24:25], off
	v_add_u32_e32 v26, 9, v14
	v_cmp_lt_i32_e32 vcc, v26, v3
	s_nop 1
	v_addc_co_u32_e64 v24, s[2:3], 9, v2, vcc
	v_ashrrev_i32_e32 v25, 31, v24
	v_lshlrev_b64 v[24:25], 10, v[24:25]
	v_lshl_add_u64 v[24:25], v[6:7], 0, v[24:25]
	global_load_ushort v49, v[24:25], off
	v_add_u32_e32 v26, 10, v14
	v_cmp_lt_i32_e32 vcc, v26, v3
	s_nop 1
	v_addc_co_u32_e64 v24, s[2:3], 10, v2, vcc
	v_ashrrev_i32_e32 v25, 31, v24
	v_lshlrev_b64 v[24:25], 10, v[24:25]
	v_lshl_add_u64 v[24:25], v[6:7], 0, v[24:25]
	global_load_ushort v50, v[24:25], off
	v_add_u32_e32 v26, 11, v14
	v_cmp_lt_i32_e32 vcc, v26, v3
	s_nop 1
	v_addc_co_u32_e64 v24, s[2:3], 11, v2, vcc
	v_ashrrev_i32_e32 v25, 31, v24
	v_lshlrev_b64 v[24:25], 10, v[24:25]
	v_lshl_add_u64 v[24:25], v[6:7], 0, v[24:25]
	global_load_ushort v51, v[24:25], off
	v_add_u32_e32 v26, 12, v14
	v_cmp_lt_i32_e32 vcc, v26, v3
	s_nop 1
	v_addc_co_u32_e64 v24, s[2:3], 12, v2, vcc
	v_ashrrev_i32_e32 v25, 31, v24
	v_lshlrev_b64 v[24:25], 10, v[24:25]
	v_lshl_add_u64 v[24:25], v[6:7], 0, v[24:25]
	global_load_ushort v52, v[24:25], off
	v_add_u32_e32 v26, 13, v14
	v_cmp_lt_i32_e32 vcc, v26, v3
	s_nop 1
	v_addc_co_u32_e64 v24, s[2:3], 13, v2, vcc
	v_ashrrev_i32_e32 v25, 31, v24
	v_lshlrev_b64 v[24:25], 10, v[24:25]
	v_lshl_add_u64 v[24:25], v[6:7], 0, v[24:25]
	global_load_ushort v53, v[24:25], off
	v_add_u32_e32 v26, 14, v14
	v_cmp_lt_i32_e32 vcc, v26, v3
	s_nop 1
	v_addc_co_u32_e64 v24, s[2:3], 14, v2, vcc
	v_ashrrev_i32_e32 v25, 31, v24
	v_lshlrev_b64 v[24:25], 10, v[24:25]
	v_lshl_add_u64 v[24:25], v[6:7], 0, v[24:25]
	global_load_ushort v54, v[24:25], off
	v_add_u32_e32 v26, 15, v14
	v_cmp_lt_i32_e32 vcc, v26, v3
	s_nop 1
	v_addc_co_u32_e64 v24, s[2:3], 15, v2, vcc
	v_ashrrev_i32_e32 v25, 31, v24
	v_lshlrev_b64 v[24:25], 10, v[24:25]
	v_lshl_add_u64 v[24:25], v[6:7], 0, v[24:25]
	global_load_ushort v55, v[24:25], off
	ds_read2_b32 v[56:57], v15 offset1:1
	ds_read2_b32 v[58:59], v15 offset0:2 offset1:3
	ds_read2_b32 v[60:61], v15 offset0:4 offset1:5
	ds_read2_b32 v[62:63], v15 offset0:6 offset1:7
	ds_read2_b32 v[64:65], v15 offset0:8 offset1:9
	ds_read2_b32 v[66:67], v15 offset0:10 offset1:11
	ds_read2_b32 v[68:69], v15 offset0:12 offset1:13
	ds_read2_b32 v[70:71], v15 offset0:14 offset1:15
	v_cmp_lt_i32_e32 vcc, v14, v3
	s_waitcnt vmcnt(15) lgkmcnt(0)
	v_lshlrev_b32_e32 v40, 16, v40
	v_mul_f32_e32 v27, v10, v18
	v_cndmask_b32_e32 v40, 0, v40, vcc
	v_fmac_f32_e32 v27, v11, v20
	v_fmac_f32_e32 v27, v12, v40
	v_add_f32_e32 v27, v13, v27
	v_mul_f32_e32 v27, v56, v27
	v_cvt_pk_bf16_f32 v27, v27, s0
	v_add_u32_e32 v24, 0, v2
	v_ashrrev_i32_e32 v25, 31, v24
	v_lshlrev_b64 v[24:25], 10, v[24:25]
	v_lshl_add_u64 v[24:25], v[4:5], 0, v[24:25]
	global_store_short v[24:25], v27, off
	v_add_u32_e32 v26, 1, v14
	v_cmp_lt_i32_e32 vcc, v26, v3
	s_waitcnt vmcnt(15)
	v_lshlrev_b32_e32 v41, 16, v41
	v_mul_f32_e32 v27, v10, v20
	v_cndmask_b32_e32 v41, 0, v41, vcc
	v_fmac_f32_e32 v27, v11, v40
	v_fmac_f32_e32 v27, v12, v41
	v_add_f32_e32 v27, v13, v27
	v_mul_f32_e32 v27, v57, v27
	v_cvt_pk_bf16_f32 v27, v27, s0
	v_add_u32_e32 v24, 1, v2
	v_ashrrev_i32_e32 v25, 31, v24
	v_lshlrev_b64 v[24:25], 10, v[24:25]
	v_lshl_add_u64 v[24:25], v[4:5], 0, v[24:25]
	global_store_short v[24:25], v27, off
	v_add_u32_e32 v26, 2, v14
	v_cmp_lt_i32_e32 vcc, v26, v3
	s_waitcnt vmcnt(15)
	v_lshlrev_b32_e32 v42, 16, v42
	v_mul_f32_e32 v27, v10, v40
	v_cndmask_b32_e32 v42, 0, v42, vcc
	v_fmac_f32_e32 v27, v11, v41
	v_fmac_f32_e32 v27, v12, v42
	v_add_f32_e32 v27, v13, v27
	v_mul_f32_e32 v27, v58, v27
	v_cvt_pk_bf16_f32 v27, v27, s0
	v_add_u32_e32 v24, 2, v2
	v_ashrrev_i32_e32 v25, 31, v24
	v_lshlrev_b64 v[24:25], 10, v[24:25]
	v_lshl_add_u64 v[24:25], v[4:5], 0, v[24:25]
	global_store_short v[24:25], v27, off
	v_add_u32_e32 v26, 3, v14
	v_cmp_lt_i32_e32 vcc, v26, v3
	s_waitcnt vmcnt(15)
	v_lshlrev_b32_e32 v43, 16, v43
	v_mul_f32_e32 v27, v10, v41
	v_cndmask_b32_e32 v43, 0, v43, vcc
	v_fmac_f32_e32 v27, v11, v42
	v_fmac_f32_e32 v27, v12, v43
	v_add_f32_e32 v27, v13, v27
	v_mul_f32_e32 v27, v59, v27
	v_cvt_pk_bf16_f32 v27, v27, s0
	v_add_u32_e32 v24, 3, v2
	v_ashrrev_i32_e32 v25, 31, v24
	v_lshlrev_b64 v[24:25], 10, v[24:25]
	v_lshl_add_u64 v[24:25], v[4:5], 0, v[24:25]
	global_store_short v[24:25], v27, off
	v_add_u32_e32 v26, 4, v14
	v_cmp_lt_i32_e32 vcc, v26, v3
	s_waitcnt vmcnt(15)
	v_lshlrev_b32_e32 v44, 16, v44
	v_mul_f32_e32 v27, v10, v42
	v_cndmask_b32_e32 v44, 0, v44, vcc
	v_fmac_f32_e32 v27, v11, v43
	v_fmac_f32_e32 v27, v12, v44
	v_add_f32_e32 v27, v13, v27
	v_mul_f32_e32 v27, v60, v27
	v_cvt_pk_bf16_f32 v27, v27, s0
	v_add_u32_e32 v24, 4, v2
	v_ashrrev_i32_e32 v25, 31, v24
	v_lshlrev_b64 v[24:25], 10, v[24:25]
	v_lshl_add_u64 v[24:25], v[4:5], 0, v[24:25]
	global_store_short v[24:25], v27, off
	v_add_u32_e32 v26, 5, v14
	v_cmp_lt_i32_e32 vcc, v26, v3
	s_waitcnt vmcnt(15)
; __device__ __forceinline__ float bf2f(bf16 b) { return __uint_as_float(((unsigned)b) << 16); }
; __device__ __forceinline__ void hy_fin_tile(const Params& p, int layer, int item, float* sT) {
;     ...
;     for (int j = 0; j < 16; ++j) {
;       const int t = ts + j;
;       const bool hn = (pos + j) < L - 1;
;       const int tn = hn ? t + 1 : t;
;       float xn = bf2f(p.hx2[(size_t)tn * 512 + c]);
;       xn = hn ? xn : 0.f;
;       float x2c = xp * w0 + xc * w1 + xn * w2 + bb;
;       p.hv[(size_t)t * 512 + c] = f2bf(x2c * sT[cl * 65 + tq * 16 + j]);
;       xp = xc; xc = xn;
;     }
;   }
;   __syncthreads();
	v_lshlrev_b32_e32 v45, 16, v45
	v_mul_f32_e32 v27, v10, v43
	v_cndmask_b32_e32 v45, 0, v45, vcc
	v_fmac_f32_e32 v27, v11, v44
	v_fmac_f32_e32 v27, v12, v45
	v_add_f32_e32 v27, v13, v27
	v_mul_f32_e32 v27, v61, v27
	v_cvt_pk_bf16_f32 v27, v27, s0
	v_add_u32_e32 v24, 5, v2
	v_ashrrev_i32_e32 v25, 31, v24
	v_lshlrev_b64 v[24:25], 10, v[24:25]
	v_lshl_add_u64 v[24:25], v[4:5], 0, v[24:25]
	global_store_short v[24:25], v27, off
	v_add_u32_e32 v26, 6, v14
	v_cmp_lt_i32_e32 vcc, v26, v3
	s_waitcnt vmcnt(15)
	v_lshlrev_b32_e32 v46, 16, v46
	v_mul_f32_e32 v27, v10, v44
	v_cndmask_b32_e32 v46, 0, v46, vcc
	v_fmac_f32_e32 v27, v11, v45
	v_fmac_f32_e32 v27, v12, v46
	v_add_f32_e32 v27, v13, v27
	v_mul_f32_e32 v27, v62, v27
	v_cvt_pk_bf16_f32 v27, v27, s0
	v_add_u32_e32 v24, 6, v2
	v_ashrrev_i32_e32 v25, 31, v24
	v_lshlrev_b64 v[24:25], 10, v[24:25]
	v_lshl_add_u64 v[24:25], v[4:5], 0, v[24:25]
	global_store_short v[24:25], v27, off
	v_add_u32_e32 v26, 7, v14
	v_cmp_lt_i32_e32 vcc, v26, v3
	s_waitcnt vmcnt(15)
	v_lshlrev_b32_e32 v47, 16, v47
	v_mul_f32_e32 v27, v10, v45
	v_cndmask_b32_e32 v47, 0, v47, vcc
	v_fmac_f32_e32 v27, v11, v46
	v_fmac_f32_e32 v27, v12, v47
	v_add_f32_e32 v27, v13, v27
	v_mul_f32_e32 v27, v63, v27
	v_cvt_pk_bf16_f32 v27, v27, s0
	v_add_u32_e32 v24, 7, v2
	v_ashrrev_i32_e32 v25, 31, v24
	v_lshlrev_b64 v[24:25], 10, v[24:25]
	v_lshl_add_u64 v[24:25], v[4:5], 0, v[24:25]
	global_store_short v[24:25], v27, off
	v_add_u32_e32 v26, 8, v14
	v_cmp_lt_i32_e32 vcc, v26, v3
	s_waitcnt vmcnt(15)
	v_lshlrev_b32_e32 v48, 16, v48
	v_mul_f32_e32 v27, v10, v46
	v_cndmask_b32_e32 v48, 0, v48, vcc
	v_fmac_f32_e32 v27, v11, v47
	v_fmac_f32_e32 v27, v12, v48
	v_add_f32_e32 v27, v13, v27
	v_mul_f32_e32 v27, v64, v27
	v_cvt_pk_bf16_f32 v27, v27, s0
	v_add_u32_e32 v24, 8, v2
	v_ashrrev_i32_e32 v25, 31, v24
	v_lshlrev_b64 v[24:25], 10, v[24:25]
	v_lshl_add_u64 v[24:25], v[4:5], 0, v[24:25]
	global_store_short v[24:25], v27, off
	v_add_u32_e32 v26, 9, v14
	v_cmp_lt_i32_e32 vcc, v26, v3
	s_waitcnt vmcnt(15)
	v_lshlrev_b32_e32 v49, 16, v49
	v_mul_f32_e32 v27, v10, v47
	v_cndmask_b32_e32 v49, 0, v49, vcc
	v_fmac_f32_e32 v27, v11, v48
	v_fmac_f32_e32 v27, v12, v49
	v_add_f32_e32 v27, v13, v27
	v_mul_f32_e32 v27, v65, v27
	v_cvt_pk_bf16_f32 v27, v27, s0
	v_add_u32_e32 v24, 9, v2
	v_ashrrev_i32_e32 v25, 31, v24
	v_lshlrev_b64 v[24:25], 10, v[24:25]
	v_lshl_add_u64 v[24:25], v[4:5], 0, v[24:25]
	global_store_short v[24:25], v27, off
	v_add_u32_e32 v26, 10, v14
	v_cmp_lt_i32_e32 vcc, v26, v3
	s_waitcnt vmcnt(15)
	v_lshlrev_b32_e32 v50, 16, v50
	v_mul_f32_e32 v27, v10, v48
	v_cndmask_b32_e32 v50, 0, v50, vcc
	v_fmac_f32_e32 v27, v11, v49
	v_fmac_f32_e32 v27, v12, v50
	v_add_f32_e32 v27, v13, v27
	v_mul_f32_e32 v27, v66, v27
	v_cvt_pk_bf16_f32 v27, v27, s0
	v_add_u32_e32 v24, 10, v2
	v_ashrrev_i32_e32 v25, 31, v24
	v_lshlrev_b64 v[24:25], 10, v[24:25]
	v_lshl_add_u64 v[24:25], v[4:5], 0, v[24:25]
	global_store_short v[24:25], v27, off
	v_add_u32_e32 v26, 11, v14
	v_cmp_lt_i32_e32 vcc, v26, v3
	s_waitcnt vmcnt(15)
	v_lshlrev_b32_e32 v51, 16, v51
	v_mul_f32_e32 v27, v10, v49
	v_cndmask_b32_e32 v51, 0, v51, vcc
	v_fmac_f32_e32 v27, v11, v50
	v_fmac_f32_e32 v27, v12, v51
	v_add_f32_e32 v27, v13, v27
	v_mul_f32_e32 v27, v67, v27
	v_cvt_pk_bf16_f32 v27, v27, s0
	v_add_u32_e32 v24, 11, v2
	v_ashrrev_i32_e32 v25, 31, v24
	v_lshlrev_b64 v[24:25], 10, v[24:25]
	v_lshl_add_u64 v[24:25], v[4:5], 0, v[24:25]
	global_store_short v[24:25], v27, off
	v_add_u32_e32 v26, 12, v14
	v_cmp_lt_i32_e32 vcc, v26, v3
	s_waitcnt vmcnt(15)
	v_lshlrev_b32_e32 v52, 16, v52
	v_mul_f32_e32 v27, v10, v50
	v_cndmask_b32_e32 v52, 0, v52, vcc
	v_fmac_f32_e32 v27, v11, v51
	v_fmac_f32_e32 v27, v12, v52
	v_add_f32_e32 v27, v13, v27
	v_mul_f32_e32 v27, v68, v27
	v_cvt_pk_bf16_f32 v27, v27, s0
	v_add_u32_e32 v24, 12, v2
	v_ashrrev_i32_e32 v25, 31, v24
	v_lshlrev_b64 v[24:25], 10, v[24:25]
	v_lshl_add_u64 v[24:25], v[4:5], 0, v[24:25]
	global_store_short v[24:25], v27, off
	v_add_u32_e32 v26, 13, v14
	v_cmp_lt_i32_e32 vcc, v26, v3
	s_waitcnt vmcnt(15)
	v_lshlrev_b32_e32 v53, 16, v53
	v_mul_f32_e32 v27, v10, v51
	v_cndmask_b32_e32 v53, 0, v53, vcc
	v_fmac_f32_e32 v27, v11, v52
	v_fmac_f32_e32 v27, v12, v53
	v_add_f32_e32 v27, v13, v27
	v_mul_f32_e32 v27, v69, v27
	v_cvt_pk_bf16_f32 v27, v27, s0
	v_add_u32_e32 v24, 13, v2
	v_ashrrev_i32_e32 v25, 31, v24
	v_lshlrev_b64 v[24:25], 10, v[24:25]
	v_lshl_add_u64 v[24:25], v[4:5], 0, v[24:25]
	global_store_short v[24:25], v27, off
	v_add_u32_e32 v26, 14, v14
	v_cmp_lt_i32_e32 vcc, v26, v3
	s_waitcnt vmcnt(15)
	v_lshlrev_b32_e32 v54, 16, v54
	v_mul_f32_e32 v27, v10, v52
	v_cndmask_b32_e32 v54, 0, v54, vcc
	v_fmac_f32_e32 v27, v11, v53
	v_fmac_f32_e32 v27, v12, v54
	v_add_f32_e32 v27, v13, v27
	v_mul_f32_e32 v27, v70, v27
	v_cvt_pk_bf16_f32 v27, v27, s0
	v_add_u32_e32 v24, 14, v2
	v_ashrrev_i32_e32 v25, 31, v24
	v_lshlrev_b64 v[24:25], 10, v[24:25]
	v_lshl_add_u64 v[24:25], v[4:5], 0, v[24:25]
	global_store_short v[24:25], v27, off
	v_add_u32_e32 v26, 15, v14
	v_cmp_lt_i32_e32 vcc, v26, v3
	s_waitcnt vmcnt(15)
	v_lshlrev_b32_e32 v55, 16, v55
	v_mul_f32_e32 v27, v10, v53
	v_cndmask_b32_e32 v55, 0, v55, vcc
	v_fmac_f32_e32 v27, v11, v54
	v_fmac_f32_e32 v27, v12, v55
	v_add_f32_e32 v27, v13, v27
	v_mul_f32_e32 v27, v71, v27
	v_cvt_pk_bf16_f32 v27, v27, s0
	v_add_u32_e32 v24, 15, v2
	v_ashrrev_i32_e32 v25, 31, v24
	v_lshlrev_b64 v[24:25], 10, v[24:25]
	v_lshl_add_u64 v[24:25], v[4:5], 0, v[24:25]
	global_store_short v[24:25], v27, off
	s_barrier

; __device__ __forceinline__ float bf2f(bf16 b) { return __uint_as_float(((unsigned)b) << 16); }
; __device__ __forceinline__ float siluf_(float x) { return x * __builtin_amdgcn_rcpf(1.f + fexp(-x)); }
; template <bool FULL, int DIR>
; __device__ __forceinline__ void gla_dir(const Params& p, int layer, int item, GlaSm& sm) {
;     ...
;           const float gn = p.in[18][layer * 128 + 32 * w + r];
; #pragma unroll
;           for (int mi2 = 0; mi2 < 2; ++mi2)
; #pragma unroll
;             for (int e = 0; e < 16; ++e) {
;               const int i = 32 * mi2 + ROW_OF(e, hh);
;               const float rs = sm.sBmid[i];
;               bf16* og = p.gog + (size_t)(t0 + i) * 512 + vcol;
;               *og = f2bf(o[mi2][e] * rs * gn * siluf_(bf2f(*og)));
.LBB0_1276:
	s_or_b64 exec, exec, s[2:3]
	v_readlane_b32 s76, v252, 41
	v_readlane_b32 s77, v252, 42
	v_readlane_b32 s78, v252, 43
	v_readlane_b32 s79, v252, 44
	v_readlane_b32 s64, v254, 18
	v_readlane_b32 s70, v254, 24
	v_readlane_b32 s71, v254, 25
	s_waitcnt lgkmcnt(0)
	s_barrier
	v_lshl_add_u64 v[12:13], v[118:119], 1, s[70:71]
	v_lshl_add_u64 v[222:223], v[12:13], 0, v[122:123]
	global_load_ushort v176, v[222:223], off
	v_lshl_add_u64 v[222:223], v[12:13], 0, v[120:121]
	global_load_ushort v177, v[222:223], off
	v_lshl_add_u64 v[222:223], v[12:13], 0, v[116:117]
	global_load_ushort v178, v[222:223], off
	v_lshl_add_u64 v[222:223], v[12:13], 0, v[114:115]
	global_load_ushort v179, v[222:223], off
	v_lshl_add_u64 v[222:223], v[12:13], 0, v[112:113]
	global_load_ushort v180, v[222:223], off
	v_lshl_add_u64 v[222:223], v[12:13], 0, v[110:111]
	global_load_ushort v181, v[222:223], off
	v_lshl_add_u64 v[222:223], v[12:13], 0, v[108:109]
	global_load_ushort v182, v[222:223], off
	v_lshl_add_u64 v[222:223], v[12:13], 0, v[106:107]
	global_load_ushort v183, v[222:223], off
	v_lshl_add_u64 v[222:223], v[12:13], 0, v[104:105]
	global_load_ushort v184, v[222:223], off
	v_lshl_add_u64 v[222:223], v[12:13], 0, v[102:103]
	global_load_ushort v185, v[222:223], off
	v_lshl_add_u64 v[222:223], v[12:13], 0, v[100:101]
	global_load_ushort v186, v[222:223], off
	v_lshl_add_u64 v[222:223], v[12:13], 0, v[98:99]
	global_load_ushort v187, v[222:223], off
	v_lshl_add_u64 v[222:223], v[12:13], 0, v[96:97]
	global_load_ushort v188, v[222:223], off
	v_lshl_add_u64 v[222:223], v[12:13], 0, v[94:95]
	global_load_ushort v189, v[222:223], off
	v_lshl_add_u64 v[222:223], v[12:13], 0, v[92:93]
	global_load_ushort v190, v[222:223], off
	v_lshl_add_u64 v[222:223], v[12:13], 0, v[90:91]
	global_load_ushort v191, v[222:223], off
	v_lshl_add_u64 v[222:223], v[12:13], 0, v[88:89]
	global_load_ushort v192, v[222:223], off
	v_lshl_add_u64 v[222:223], v[12:13], 0, v[86:87]
	global_load_ushort v193, v[222:223], off
	v_lshl_add_u64 v[222:223], v[12:13], 0, v[84:85]
	global_load_ushort v196, v[222:223], off
	v_lshl_add_u64 v[222:223], v[12:13], 0, v[82:83]
	global_load_ushort v197, v[222:223], off
	v_lshl_add_u64 v[222:223], v[12:13], 0, v[80:81]
	global_load_ushort v198, v[222:223], off
	v_lshl_add_u64 v[222:223], v[12:13], 0, v[32:33]
	global_load_ushort v199, v[222:223], off
	v_lshl_add_u64 v[222:223], v[12:13], 0, v[30:31]
	global_load_ushort v200, v[222:223], off
	v_lshl_add_u64 v[222:223], v[12:13], 0, v[28:29]
	global_load_ushort v201, v[222:223], off
	v_lshl_add_u64 v[222:223], v[12:13], 0, v[26:27]
	global_load_ushort v202, v[222:223], off
	v_lshl_add_u64 v[222:223], v[12:13], 0, v[24:25]
	global_load_ushort v203, v[222:223], off
	v_lshl_add_u64 v[222:223], v[12:13], 0, v[22:23]
	global_load_ushort v204, v[222:223], off
	v_lshl_add_u64 v[222:223], v[12:13], 0, v[20:21]
	global_load_ushort v205, v[222:223], off
	v_lshl_add_u64 v[222:223], v[12:13], 0, v[18:19]
	global_load_ushort v206, v[222:223], off
	v_lshl_add_u64 v[222:223], v[12:13], 0, v[10:11]
	global_load_ushort v207, v[222:223], off
	v_lshl_add_u64 v[222:223], v[12:13], 0, v[8:9]
	global_load_ushort v208, v[222:223], off
	v_lshl_add_u64 v[222:223], v[12:13], 0, v[6:7]
	global_load_ushort v209, v[222:223], off
	v_lshl_add_u64 v[122:123], v[12:13], 0, v[122:123]
	v_readlane_b32 s2, v254, 62
	v_readlane_b32 s80, v252, 45
	v_readlane_b32 s81, v252, 46
	v_add_u32_e32 v2, s2, v157
	v_or_b32_e32 v2, v2, v155
	v_ashrrev_i32_e32 v3, 31, v2
	v_lshl_add_u64 v[2:3], v[2:3], 2, s[80:81]
	global_load_dword v17, v[2:3], off
	v_lshlrev_b32_e32 v118, 2, v156
	v_or_b32_e32 v2, 0x11000, v118
	ds_read_b128 v[2:5], v2
	v_lshl_add_u64 v[120:121], v[12:13], 0, v[120:121]
	v_lshl_add_u64 v[112:113], v[12:13], 0, v[112:113]
	v_lshl_add_u64 v[110:111], v[12:13], 0, v[110:111]
	v_lshl_add_u64 v[104:105], v[12:13], 0, v[104:105]
	s_waitcnt lgkmcnt(0)
	v_mul_f32_e32 v2, v168, v2
	v_mul_f32_e32 v4, v166, v4
	v_lshl_add_u64 v[102:103], v[12:13], 0, v[102:103]
	v_lshl_add_u64 v[96:97], v[12:13], 0, v[96:97]
	v_lshl_add_u64 v[94:95], v[12:13], 0, v[94:95]
	v_lshl_add_u64 v[88:89], v[12:13], 0, v[88:89]
	v_lshl_add_u64 v[86:87], v[12:13], 0, v[86:87]
	v_lshl_add_u64 v[80:81], v[12:13], 0, v[80:81]
	v_lshl_add_u64 v[32:33], v[12:13], 0, v[32:33]
	v_lshl_add_u64 v[26:27], v[12:13], 0, v[26:27]
	v_lshl_add_u64 v[24:25], v[12:13], 0, v[24:25]
	v_lshl_add_u64 v[18:19], v[12:13], 0, v[18:19]
	v_lshl_add_u64 v[10:11], v[12:13], 0, v[10:11]
	v_mul_u32_u24_e32 v14, 0x90, v155
	v_readlane_b32 s82, v252, 47
	v_readlane_b32 s83, v252, 48
	v_readlane_b32 s84, v252, 49
	v_readlane_b32 s85, v252, 50
	v_readlane_b32 s86, v252, 51
	v_readlane_b32 s87, v252, 52
	v_readlane_b32 s88, v252, 53
	v_readlane_b32 s89, v252, 54
	v_readlane_b32 s90, v252, 55
	v_readlane_b32 s91, v252, 56
	v_readlane_b32 s65, v254, 19
	v_readlane_b32 s66, v254, 20
	v_readlane_b32 s67, v254, 21
	v_readlane_b32 s68, v254, 22
	v_readlane_b32 s69, v254, 23
	v_readlane_b32 s72, v254, 26
	v_readlane_b32 s73, v254, 27
	v_readlane_b32 s74, v254, 28
	v_readlane_b32 s75, v254, 29
	v_readlane_b32 s76, v254, 30
	v_readlane_b32 s77, v254, 31
	v_readlane_b32 s78, v254, 32
	v_readlane_b32 s79, v254, 33
	s_waitcnt vmcnt(0)
	v_mov_b32_e32 v119, v176
	v_lshlrev_b32_e32 v119, 16, v119
	v_mul_f32_e32 v124, 0xbfb8aa3b, v119
	v_exp_f32_e32 v124, v124
	s_waitcnt vmcnt(0)
; __device__ __forceinline__ float bf2f(bf16 b) { return __uint_as_float(((unsigned)b) << 16); }
; __device__ __forceinline__ float siluf_(float x) { return x * __builtin_amdgcn_rcpf(1.f + fexp(-x)); }
; template <bool FULL, int DIR>
; __device__ __forceinline__ void gla_dir(const Params& p, int layer, int item, GlaSm& sm) {
;     ...
; #pragma unroll
;           for (int mi2 = 0; mi2 < 2; ++mi2)
; #pragma unroll
;             for (int e = 0; e < 16; ++e) {
;               const int i = 32 * mi2 + ROW_OF(e, hh);
;               const float rs = sm.sBmid[i];
;               bf16* og = p.gog + (size_t)(t0 + i) * 512 + vcol;
;               *og = f2bf(o[mi2][e] * rs * gn * siluf_(bf2f(*og)));
	v_mul_f32_e32 v2, v17, v2
	v_add_f32_e32 v124, 1.0, v124
	v_rcp_f32_e32 v124, v124
	v_mul_f32_e32 v4, v17, v4
	v_mul_f32_e32 v119, v124, v119
	v_mul_f32_e32 v2, v2, v119
	v_cvt_pk_bf16_f32 v2, v2, s0
	global_store_short v[122:123], v2, off
	v_mul_f32_e32 v2, v167, v3
	v_mul_f32_e32 v2, v17, v2
	v_mov_b32_e32 v3, v177
	v_lshlrev_b32_e32 v3, 16, v3
	v_mul_f32_e32 v119, 0xbfb8aa3b, v3
	v_exp_f32_e32 v119, v119
	s_nop 0
	v_add_f32_e32 v119, 1.0, v119
	v_rcp_f32_e32 v119, v119
	s_nop 0
	v_mul_f32_e32 v3, v119, v3
	v_mul_f32_e32 v2, v2, v3
	v_cvt_pk_bf16_f32 v2, v2, s0
	global_store_short v[120:121], v2, off
	v_lshl_add_u64 v[2:3], v[12:13], 0, v[116:117]
	v_mov_b32_e32 v116, v178
	v_lshlrev_b32_e32 v116, 16, v116
	v_mul_f32_e32 v117, 0xbfb8aa3b, v116
	v_exp_f32_e32 v117, v117
	s_nop 0
	v_add_f32_e32 v117, 1.0, v117
	v_rcp_f32_e32 v117, v117
	s_nop 0
	v_mul_f32_e32 v116, v117, v116
	v_mul_f32_e32 v4, v4, v116
	v_cvt_pk_bf16_f32 v4, v4, s0
	global_store_short v[2:3], v4, off
	v_lshl_add_u64 v[2:3], v[12:13], 0, v[114:115]
	v_mul_f32_e32 v4, v165, v5
	v_mul_f32_e32 v4, v17, v4
	v_mov_b32_e32 v5, v179
	v_lshlrev_b32_e32 v5, 16, v5
	v_mul_f32_e32 v114, 0xbfb8aa3b, v5
	v_exp_f32_e32 v114, v114
	s_nop 0
	v_add_f32_e32 v114, 1.0, v114
	v_rcp_f32_e32 v114, v114
	s_nop 0
	v_mul_f32_e32 v5, v114, v5
	v_mul_f32_e32 v4, v4, v5
	v_cvt_pk_bf16_f32 v4, v4, s0
	global_store_short v[2:3], v4, off
	v_or_b32_e32 v2, 0x11020, v118
	ds_read_b128 v[2:5], v2
	s_waitcnt lgkmcnt(0)
	v_mul_f32_e32 v2, v164, v2
	v_mul_f32_e32 v2, v17, v2
	v_mul_f32_e32 v4, v162, v4
	v_mul_f32_e32 v4, v17, v4
	v_mov_b32_e32 v114, v180
	v_lshlrev_b32_e32 v114, 16, v114
	v_mul_f32_e32 v115, 0xbfb8aa3b, v114
	v_exp_f32_e32 v115, v115
	s_nop 0
	v_add_f32_e32 v115, 1.0, v115
	v_rcp_f32_e32 v115, v115
	s_nop 0
	v_mul_f32_e32 v114, v115, v114
	v_mul_f32_e32 v2, v2, v114
	v_cvt_pk_bf16_f32 v2, v2, s0
	global_store_short v[112:113], v2, off
	v_mul_f32_e32 v2, v163, v3
	v_mul_f32_e32 v2, v17, v2
	v_mov_b32_e32 v3, v181
	v_lshlrev_b32_e32 v3, 16, v3
	v_mul_f32_e32 v112, 0xbfb8aa3b, v3
	v_exp_f32_e32 v112, v112
	s_nop 0
	v_add_f32_e32 v112, 1.0, v112
	v_rcp_f32_e32 v112, v112
	s_nop 0
	v_mul_f32_e32 v3, v112, v3
	v_mul_f32_e32 v2, v2, v3
	v_cvt_pk_bf16_f32 v2, v2, s0
	global_store_short v[110:111], v2, off
	v_lshl_add_u64 v[2:3], v[12:13], 0, v[108:109]
	v_mov_b32_e32 v108, v182
	v_lshlrev_b32_e32 v108, 16, v108
	v_mul_f32_e32 v109, 0xbfb8aa3b, v108
	v_exp_f32_e32 v109, v109
	s_nop 0
	v_add_f32_e32 v109, 1.0, v109
	v_rcp_f32_e32 v109, v109
	s_nop 0
	v_mul_f32_e32 v108, v109, v108
	v_mul_f32_e32 v4, v4, v108
	v_cvt_pk_bf16_f32 v4, v4, s0
	global_store_short v[2:3], v4, off
	v_lshl_add_u64 v[2:3], v[12:13], 0, v[106:107]
	v_mul_f32_e32 v4, v161, v5
	v_mul_f32_e32 v4, v17, v4
	v_mov_b32_e32 v5, v183
	v_lshlrev_b32_e32 v5, 16, v5
	v_mul_f32_e32 v106, 0xbfb8aa3b, v5
	v_exp_f32_e32 v106, v106
	s_nop 0
	v_add_f32_e32 v106, 1.0, v106
	v_rcp_f32_e32 v106, v106
	s_nop 0
	v_mul_f32_e32 v5, v106, v5
	v_mul_f32_e32 v4, v4, v5
	v_cvt_pk_bf16_f32 v4, v4, s0
	global_store_short v[2:3], v4, off
	v_or_b32_e32 v2, 0x11040, v118
	ds_read_b128 v[2:5], v2
	s_waitcnt lgkmcnt(0)
	v_mul_f32_e32 v2, v160, v2
	v_mul_f32_e32 v2, v17, v2
	v_mul_f32_e32 v4, v158, v4
	v_mul_f32_e32 v4, v17, v4
	v_mov_b32_e32 v106, v184
	v_lshlrev_b32_e32 v106, 16, v106
	v_mul_f32_e32 v107, 0xbfb8aa3b, v106
	v_exp_f32_e32 v107, v107
	s_nop 0
	v_add_f32_e32 v107, 1.0, v107
	v_rcp_f32_e32 v107, v107
	s_nop 0
	v_mul_f32_e32 v106, v107, v106
	v_mul_f32_e32 v2, v2, v106
	v_cvt_pk_bf16_f32 v2, v2, s0
	global_store_short v[104:105], v2, off
	v_mul_f32_e32 v2, v159, v3
	v_mul_f32_e32 v2, v17, v2
	v_mov_b32_e32 v3, v185
	v_lshlrev_b32_e32 v3, 16, v3
	v_mul_f32_e32 v104, 0xbfb8aa3b, v3
	v_exp_f32_e32 v104, v104
	s_nop 0
	v_add_f32_e32 v104, 1.0, v104
	v_rcp_f32_e32 v104, v104
	s_nop 0
	v_mul_f32_e32 v3, v104, v3
	v_mul_f32_e32 v2, v2, v3
	v_cvt_pk_bf16_f32 v2, v2, s0
	global_store_short v[102:103], v2, off
	v_lshl_add_u64 v[2:3], v[12:13], 0, v[100:101]
	v_mov_b32_e32 v100, v186
	v_lshlrev_b32_e32 v100, 16, v100
	v_mul_f32_e32 v101, 0xbfb8aa3b, v100
	v_exp_f32_e32 v101, v101
	s_nop 0
	v_add_f32_e32 v101, 1.0, v101
	v_rcp_f32_e32 v101, v101
	s_nop 0
	v_mul_f32_e32 v100, v101, v100
	v_mul_f32_e32 v4, v4, v100
	v_cvt_pk_bf16_f32 v4, v4, s0
	global_store_short v[2:3], v4, off
	v_lshl_add_u64 v[2:3], v[12:13], 0, v[98:99]
	v_mul_f32_e32 v4, v154, v5
	v_mul_f32_e32 v4, v17, v4
	v_mov_b32_e32 v5, v187
	v_lshlrev_b32_e32 v5, 16, v5
	v_mul_f32_e32 v98, 0xbfb8aa3b, v5
	v_exp_f32_e32 v98, v98
	s_nop 0
	v_add_f32_e32 v98, 1.0, v98
	v_rcp_f32_e32 v98, v98
	s_nop 0
	v_mul_f32_e32 v5, v98, v5
	v_mul_f32_e32 v4, v4, v5
	v_cvt_pk_bf16_f32 v4, v4, s0
	global_store_short v[2:3], v4, off
	v_or_b32_e32 v2, 0x11060, v118
	ds_read_b128 v[2:5], v2
	s_waitcnt lgkmcnt(0)
	v_mul_f32_e32 v2, v153, v2
	v_mul_f32_e32 v2, v17, v2
	v_mul_f32_e32 v4, v151, v4
	v_mul_f32_e32 v4, v17, v4
	v_mov_b32_e32 v98, v188
	v_lshlrev_b32_e32 v98, 16, v98
	v_mul_f32_e32 v99, 0xbfb8aa3b, v98
	v_exp_f32_e32 v99, v99
	s_nop 0
	v_add_f32_e32 v99, 1.0, v99
	v_rcp_f32_e32 v99, v99
	s_nop 0
	v_mul_f32_e32 v98, v99, v98
	v_mul_f32_e32 v2, v2, v98
	v_cvt_pk_bf16_f32 v2, v2, s0
	global_store_short v[96:97], v2, off
	v_mul_f32_e32 v2, v152, v3
	v_mul_f32_e32 v2, v17, v2
	v_mov_b32_e32 v3, v189
	v_lshlrev_b32_e32 v3, 16, v3
	v_mul_f32_e32 v96, 0xbfb8aa3b, v3
	v_exp_f32_e32 v96, v96
	s_nop 0
	v_add_f32_e32 v96, 1.0, v96
	v_rcp_f32_e32 v96, v96
	s_nop 0
	v_mul_f32_e32 v3, v96, v3
	v_mul_f32_e32 v2, v2, v3
	v_cvt_pk_bf16_f32 v2, v2, s0
	global_store_short v[94:95], v2, off
	v_lshl_add_u64 v[2:3], v[12:13], 0, v[92:93]
	v_mov_b32_e32 v92, v190
	v_lshlrev_b32_e32 v92, 16, v92
	v_mul_f32_e32 v93, 0xbfb8aa3b, v92
	v_exp_f32_e32 v93, v93
	s_nop 0
	v_add_f32_e32 v93, 1.0, v93
	v_rcp_f32_e32 v93, v93
	s_nop 0
	v_mul_f32_e32 v92, v93, v92
	v_mul_f32_e32 v4, v4, v92
	v_cvt_pk_bf16_f32 v4, v4, s0
	global_store_short v[2:3], v4, off
	v_lshl_add_u64 v[2:3], v[12:13], 0, v[90:91]
	v_mul_f32_e32 v4, v150, v5
	v_mul_f32_e32 v4, v17, v4
	v_mov_b32_e32 v5, v191
	v_lshlrev_b32_e32 v5, 16, v5
	v_mul_f32_e32 v90, 0xbfb8aa3b, v5
	v_exp_f32_e32 v90, v90
	s_nop 0
	v_add_f32_e32 v90, 1.0, v90
	v_rcp_f32_e32 v90, v90
	s_nop 0
	v_mul_f32_e32 v5, v90, v5
	v_mul_f32_e32 v4, v4, v5
	v_cvt_pk_bf16_f32 v4, v4, s0
	global_store_short v[2:3], v4, off
	v_or_b32_e32 v2, 0x11080, v118
	ds_read_b128 v[2:5], v2
	s_waitcnt lgkmcnt(0)
; __device__ __forceinline__ float bf2f(bf16 b) { return __uint_as_float(((unsigned)b) << 16); }
; __device__ __forceinline__ float siluf_(float x) { return x * __builtin_amdgcn_rcpf(1.f + fexp(-x)); }
; template <bool FULL, int DIR>
; __device__ __forceinline__ void gla_dir(const Params& p, int layer, int item, GlaSm& sm) {
;     ...
; #pragma unroll
;           for (int mi2 = 0; mi2 < 2; ++mi2)
; #pragma unroll
;             for (int e = 0; e < 16; ++e) {
;               const int i = 32 * mi2 + ROW_OF(e, hh);
;               const float rs = sm.sBmid[i];
;               bf16* og = p.gog + (size_t)(t0 + i) * 512 + vcol;
;               *og = f2bf(o[mi2][e] * rs * gn * siluf_(bf2f(*og)));
	v_mul_f32_e32 v2, v149, v2
	v_mul_f32_e32 v2, v17, v2
	v_mul_f32_e32 v4, v147, v4
	v_mul_f32_e32 v4, v17, v4
	v_mov_b32_e32 v90, v192
	v_lshlrev_b32_e32 v90, 16, v90
	v_mul_f32_e32 v91, 0xbfb8aa3b, v90
	v_exp_f32_e32 v91, v91
	s_nop 0
	v_add_f32_e32 v91, 1.0, v91
	v_rcp_f32_e32 v91, v91
	s_nop 0
	v_mul_f32_e32 v90, v91, v90
	v_mul_f32_e32 v2, v2, v90
	v_cvt_pk_bf16_f32 v2, v2, s0
	global_store_short v[88:89], v2, off
	v_mul_f32_e32 v2, v148, v3
	v_mul_f32_e32 v2, v17, v2
	v_mov_b32_e32 v3, v193
	v_lshlrev_b32_e32 v3, 16, v3
	v_mul_f32_e32 v88, 0xbfb8aa3b, v3
	v_exp_f32_e32 v88, v88
	s_nop 0
	v_add_f32_e32 v88, 1.0, v88
	v_rcp_f32_e32 v88, v88
	s_nop 0
	v_mul_f32_e32 v3, v88, v3
	v_mul_f32_e32 v2, v2, v3
	v_cvt_pk_bf16_f32 v2, v2, s0
	global_store_short v[86:87], v2, off
	v_lshl_add_u64 v[2:3], v[12:13], 0, v[84:85]
	v_mov_b32_e32 v84, v196
	v_lshlrev_b32_e32 v84, 16, v84
	v_mul_f32_e32 v85, 0xbfb8aa3b, v84
	v_exp_f32_e32 v85, v85
	s_nop 0
	v_add_f32_e32 v85, 1.0, v85
	v_rcp_f32_e32 v85, v85
	s_nop 0
	v_mul_f32_e32 v84, v85, v84
	v_mul_f32_e32 v4, v4, v84
	v_cvt_pk_bf16_f32 v4, v4, s0
	global_store_short v[2:3], v4, off
	v_lshl_add_u64 v[2:3], v[12:13], 0, v[82:83]
	v_mul_f32_e32 v4, v146, v5
	v_mul_f32_e32 v4, v17, v4
	v_mov_b32_e32 v5, v197
	v_lshlrev_b32_e32 v5, 16, v5
	v_mul_f32_e32 v82, 0xbfb8aa3b, v5
	v_exp_f32_e32 v82, v82
	s_nop 0
	v_add_f32_e32 v82, 1.0, v82
	v_rcp_f32_e32 v82, v82
	s_nop 0
	v_mul_f32_e32 v5, v82, v5
	v_mul_f32_e32 v4, v4, v5
	v_cvt_pk_bf16_f32 v4, v4, s0
	global_store_short v[2:3], v4, off
	v_or_b32_e32 v2, 0x110a0, v118
	ds_read_b128 v[2:5], v2
	s_waitcnt lgkmcnt(0)
	v_mul_f32_e32 v2, v145, v2
	v_mul_f32_e32 v2, v17, v2
	v_mul_f32_e32 v4, v143, v4
	v_mul_f32_e32 v4, v17, v4
	v_mov_b32_e32 v82, v198
	v_lshlrev_b32_e32 v82, 16, v82
	v_mul_f32_e32 v83, 0xbfb8aa3b, v82
	v_exp_f32_e32 v83, v83
	s_nop 0
	v_add_f32_e32 v83, 1.0, v83
	v_rcp_f32_e32 v83, v83
	s_nop 0
	v_mul_f32_e32 v82, v83, v82
	v_mul_f32_e32 v2, v2, v82
	v_cvt_pk_bf16_f32 v2, v2, s0
	global_store_short v[80:81], v2, off
	v_mul_f32_e32 v2, v144, v3
	v_mul_f32_e32 v2, v17, v2
	v_mov_b32_e32 v3, v199
	v_lshlrev_b32_e32 v3, 16, v3
	v_mul_f32_e32 v80, 0xbfb8aa3b, v3
	v_exp_f32_e32 v80, v80
	s_nop 0
	v_add_f32_e32 v80, 1.0, v80
	v_rcp_f32_e32 v80, v80
	s_nop 0
	v_mul_f32_e32 v3, v80, v3
	v_mul_f32_e32 v2, v2, v3
	v_cvt_pk_bf16_f32 v2, v2, s0
	global_store_short v[32:33], v2, off
	v_lshl_add_u64 v[2:3], v[12:13], 0, v[30:31]
	v_mov_b32_e32 v30, v200
	v_lshlrev_b32_e32 v30, 16, v30
	v_mul_f32_e32 v31, 0xbfb8aa3b, v30
	v_exp_f32_e32 v31, v31
	s_nop 0
	v_add_f32_e32 v31, 1.0, v31
	v_rcp_f32_e32 v31, v31
	s_nop 0
	v_mul_f32_e32 v30, v31, v30
	v_mul_f32_e32 v4, v4, v30
	v_cvt_pk_bf16_f32 v4, v4, s0
	global_store_short v[2:3], v4, off
	v_lshl_add_u64 v[2:3], v[12:13], 0, v[28:29]
	v_mul_f32_e32 v4, v142, v5
	v_mul_f32_e32 v4, v17, v4
	v_mov_b32_e32 v5, v201
	v_lshlrev_b32_e32 v5, 16, v5
	v_mul_f32_e32 v28, 0xbfb8aa3b, v5
	v_exp_f32_e32 v28, v28
	s_nop 0
	v_add_f32_e32 v28, 1.0, v28
	v_rcp_f32_e32 v28, v28
	s_nop 0
	v_mul_f32_e32 v5, v28, v5
	v_mul_f32_e32 v4, v4, v5
	v_cvt_pk_bf16_f32 v4, v4, s0
	global_store_short v[2:3], v4, off
	v_or_b32_e32 v2, 0x110c0, v118
	ds_read_b128 v[2:5], v2
	s_waitcnt lgkmcnt(0)
	v_mul_f32_e32 v2, v141, v2
	v_mul_f32_e32 v2, v17, v2
	v_mul_f32_e32 v4, v139, v4
	v_mul_f32_e32 v4, v17, v4
	v_mov_b32_e32 v28, v202
	v_lshlrev_b32_e32 v28, 16, v28
	v_mul_f32_e32 v29, 0xbfb8aa3b, v28
	v_exp_f32_e32 v29, v29
	s_nop 0
	v_add_f32_e32 v29, 1.0, v29
	v_rcp_f32_e32 v29, v29
	s_nop 0
	v_mul_f32_e32 v28, v29, v28
	v_mul_f32_e32 v2, v2, v28
	v_cvt_pk_bf16_f32 v2, v2, s0
	global_store_short v[26:27], v2, off
	v_mul_f32_e32 v2, v140, v3
	v_mul_f32_e32 v2, v17, v2
	v_mov_b32_e32 v3, v203
	v_lshlrev_b32_e32 v3, 16, v3
	v_mul_f32_e32 v26, 0xbfb8aa3b, v3
	v_exp_f32_e32 v26, v26
	s_nop 0
	v_add_f32_e32 v26, 1.0, v26
	v_rcp_f32_e32 v26, v26
	s_nop 0
	v_mul_f32_e32 v3, v26, v3
	v_mul_f32_e32 v2, v2, v3
	v_cvt_pk_bf16_f32 v2, v2, s0
	global_store_short v[24:25], v2, off
	v_lshl_add_u64 v[2:3], v[12:13], 0, v[22:23]
	v_mov_b32_e32 v22, v204
	v_lshlrev_b32_e32 v22, 16, v22
	v_mul_f32_e32 v23, 0xbfb8aa3b, v22
	v_exp_f32_e32 v23, v23
	s_nop 0
	v_add_f32_e32 v23, 1.0, v23
	v_rcp_f32_e32 v23, v23
	s_nop 0
	v_mul_f32_e32 v22, v23, v22
	v_mul_f32_e32 v4, v4, v22
	v_cvt_pk_bf16_f32 v4, v4, s0
	global_store_short v[2:3], v4, off
	v_lshl_add_u64 v[2:3], v[12:13], 0, v[20:21]
	v_mul_f32_e32 v4, v138, v5
	v_mul_f32_e32 v4, v17, v4
	v_mov_b32_e32 v5, v205
	v_lshlrev_b32_e32 v5, 16, v5
	v_mul_f32_e32 v20, 0xbfb8aa3b, v5
	v_exp_f32_e32 v20, v20
	s_nop 0
	v_add_f32_e32 v20, 1.0, v20
	v_rcp_f32_e32 v20, v20
	s_nop 0
	v_mul_f32_e32 v5, v20, v5
	v_mul_f32_e32 v4, v4, v5
	v_cvt_pk_bf16_f32 v4, v4, s0
	global_store_short v[2:3], v4, off
	v_or_b32_e32 v2, 0x110e0, v118
	ds_read_b128 v[2:5], v2
	s_waitcnt lgkmcnt(0)
; #define MFMA(a, b, c) __builtin_amdgcn_mfma_f32_32x32x16_bf16((a), (b), (c), 0, 0, 0)
; __device__ __forceinline__ float bf2f(bf16 b) { return __uint_as_float(((unsigned)b) << 16); }
; __device__ __forceinline__ float siluf_(float x) { return x * __builtin_amdgcn_rcpf(1.f + fexp(-x)); }
; template <bool FULL, int DIR>
; __device__ __forceinline__ void gla_dir(const Params& p, int layer, int item, GlaSm& sm) {
;     ...
; #pragma unroll
;           for (int mi2 = 0; mi2 < 2; ++mi2)
; #pragma unroll
;             for (int e = 0; e < 16; ++e) {
;               const int i = 32 * mi2 + ROW_OF(e, hh);
;               const float rs = sm.sBmid[i];
;               bf16* og = p.gog + (size_t)(t0 + i) * 512 + vcol;
;               *og = f2bf(o[mi2][e] * rs * gn * siluf_(bf2f(*og)));
;     ...
;       {
;         f16v U[2];
; #pragma unroll
;         for (int dt = 0; dt < 2; ++dt)
; #pragma unroll
;           for (int e = 0; e < 16; ++e) U[dt][e] = 0.f;
; #pragma unroll
;         for (int ks = 0; ks < 4; ++ks) {
;           s8v b = *(const s8v*)(sm.sVT + (32 * w + r) * 72 + 16 * ks + 8 * hh);
; #pragma unroll
;           for (int dt = 0; dt < 2; ++dt) {
;             s8v a = *(const s8v*)(sm.sKUT + (32 * dt + r) * 72 + 16 * ks + 8 * hh);
;             U[dt] = MFMA(a, b, U[dt]);
;           }
;         }
; #pragma unroll
;         for (int dt = 0; dt < 2; ++dt)
; #pragma unroll
;           for (int e = 0; e < 16; ++e) Sacc[dt][e] = sm.sDec[32 * dt + ROW_OF(e, hh)] * Sacc[dt][e] + U[dt][e];
	v_mul_f32_e32 v2, v137, v2
	v_mul_f32_e32 v2, v17, v2
	v_mul_f32_e32 v4, v16, v4
	v_mul_f32_e32 v4, v17, v4
	v_mov_b32_e32 v20, v206
	v_lshlrev_b32_e32 v20, 16, v20
	v_mul_f32_e32 v21, 0xbfb8aa3b, v20
	v_exp_f32_e32 v21, v21
	s_nop 0
	v_add_f32_e32 v21, 1.0, v21
	v_rcp_f32_e32 v21, v21
	s_nop 0
	v_mul_f32_e32 v20, v21, v20
	v_mul_f32_e32 v2, v2, v20
	v_cvt_pk_bf16_f32 v2, v2, s0
	global_store_short v[18:19], v2, off
	v_mul_f32_e32 v2, v79, v3
	v_mul_f32_e32 v2, v17, v2
	v_mov_b32_e32 v3, v207
	v_lshlrev_b32_e32 v3, 16, v3
	v_mul_f32_e32 v18, 0xbfb8aa3b, v3
	v_exp_f32_e32 v18, v18
	s_nop 0
	v_add_f32_e32 v18, 1.0, v18
	v_rcp_f32_e32 v18, v18
	s_nop 0
	v_mul_f32_e32 v3, v18, v3
	v_mul_f32_e32 v2, v2, v3
	v_cvt_pk_bf16_f32 v2, v2, s0
	global_store_short v[10:11], v2, off
	v_lshl_add_u64 v[2:3], v[12:13], 0, v[8:9]
	v_mov_b32_e32 v8, v208
	v_lshlrev_b32_e32 v8, 16, v8
	v_mul_f32_e32 v9, 0xbfb8aa3b, v8
	v_exp_f32_e32 v9, v9
	s_nop 0
	v_add_f32_e32 v9, 1.0, v9
	v_rcp_f32_e32 v9, v9
	s_nop 0
	v_mul_f32_e32 v8, v9, v8
	v_mul_f32_e32 v4, v4, v8
	v_cvt_pk_bf16_f32 v4, v4, s0
	global_store_short v[2:3], v4, off
	v_lshl_add_u64 v[2:3], v[12:13], 0, v[6:7]
	v_mul_f32_e32 v4, v15, v5
	v_mul_f32_e32 v4, v17, v4
	v_mov_b32_e32 v5, v209
	v_lshlrev_b32_e32 v5, 16, v5
	v_mul_f32_e32 v6, 0xbfb8aa3b, v5
	v_exp_f32_e32 v6, v6
	s_nop 0
	v_add_f32_e32 v6, 1.0, v6
	v_rcp_f32_e32 v6, v6
	s_nop 0
	v_mul_f32_e32 v5, v6, v5
	v_mul_f32_e32 v4, v4, v5
	v_cvt_pk_bf16_f32 v4, v4, s0
	global_store_short v[2:3], v4, off
	v_add_u32_e32 v88, v0, v14
	ds_read_b128 v[2:5], v78 offset:36864
	ds_read_b128 v[80:83], v78 offset:36896
	ds_read_b128 v[6:9], v88 offset:27648
	ds_read_b128 v[84:87], v88 offset:27680
	v_or_b32_e32 v90, 0x11260, v0
	s_sub_i32 s26, s26, 64
	s_waitcnt lgkmcnt(1)
	v_mfma_f32_32x32x16_bf16 v[18:33], v[6:9], v[2:5], 0
	ds_read_b128 v[6:9], v88 offset:32256
	s_add_u32 s22, s22, 0xffffffc0
	s_addc_u32 s23, s23, -1
	v_readlane_b32 s24, v255, 13
	s_cmpk_eq_i32 s26, 0xff00
	v_readlane_b32 s25, v255, 14
	s_waitcnt lgkmcnt(1)
	v_mfma_f32_32x32x16_bf16 v[18:33], v[84:87], v[80:83], v[18:33]
	ds_read_b128 v[84:87], v88 offset:32288
	s_waitcnt lgkmcnt(1)
	v_mfma_f32_32x32x16_bf16 v[2:17], v[6:9], v[2:5], 0
	s_waitcnt lgkmcnt(0)
	v_mfma_f32_32x32x16_bf16 v[2:17], v[84:87], v[80:83], v[2:17]
	ds_read_b128 v[80:83], v78 offset:36928
	ds_read_b128 v[84:87], v88 offset:27712
	s_waitcnt lgkmcnt(0)
	v_mfma_f32_32x32x16_bf16 v[18:33], v[84:87], v[80:83], v[18:33]
	ds_read_b128 v[84:87], v88 offset:32320
	s_waitcnt lgkmcnt(0)
	v_mfma_f32_32x32x16_bf16 v[2:17], v[84:87], v[80:83], v[2:17]
	ds_read_b128 v[78:81], v78 offset:36960
	ds_read_b128 v[82:85], v88 offset:27744
	v_or_b32_e32 v86, 0x11240, v0
	ds_read_b128 v[90:93], v90
	s_waitcnt lgkmcnt(1)
	v_mfma_f32_32x32x16_bf16 v[18:33], v[82:85], v[78:81], v[18:33]
	ds_read_b128 v[82:85], v88 offset:32352
	ds_read_b128 v[86:89], v86
	s_waitcnt lgkmcnt(1)
	v_mfma_f32_32x32x16_bf16 v[2:17], v[82:85], v[78:81], v[2:17]
	v_or_b32_e32 v78, 0x11200, v0
	ds_read_b128 v[78:81], v78
	v_or_b32_e32 v82, 0x11220, v0
	ds_read_b128 v[82:85], v82
	s_waitcnt lgkmcnt(2)
	s_nop 2
	v_pk_fma_f32 v[54:55], v[54:55], v[86:87], v[26:27]
	v_or_b32_e32 v26, 0x112c0, v0
	s_waitcnt lgkmcnt(1)
	v_pk_fma_f32 v[46:47], v[46:47], v[78:79], v[18:19]
	v_or_b32_e32 v18, 0x11280, v0
	s_waitcnt lgkmcnt(0)
	v_pk_fma_f32 v[50:51], v[50:51], v[82:83], v[22:23]
	v_pk_fma_f32 v[48:49], v[48:49], v[80:81], v[20:21]
	ds_read_b128 v[18:21], v18
	v_or_b32_e32 v22, 0x112a0, v0
	v_or_b32_e32 v0, 0x112e0, v0
	v_pk_fma_f32 v[60:61], v[60:61], v[92:93], v[32:33]
	v_pk_fma_f32 v[58:59], v[58:59], v[90:91], v[30:31]
	v_pk_fma_f32 v[56:57], v[56:57], v[88:89], v[28:29]
	v_pk_fma_f32 v[52:53], v[52:53], v[84:85], v[24:25]
	ds_read_b128 v[22:25], v22
	ds_read_b128 v[26:29], v26
	ds_read_b128 v[30:33], v0
	s_waitcnt lgkmcnt(3)
	v_pk_fma_f32 v[64:65], v[64:65], v[20:21], v[4:5]
	v_pk_fma_f32 v[62:63], v[62:63], v[18:19], v[2:3]
	v_mov_b64_e32 v[2:3], v[34:35]
	s_waitcnt lgkmcnt(1)
	v_pk_fma_f32 v[72:73], v[72:73], v[28:29], v[12:13]
	s_waitcnt lgkmcnt(0)
	v_pk_fma_f32 v[76:77], v[76:77], v[32:33], v[16:17]
	v_pk_fma_f32 v[74:75], v[74:75], v[30:31], v[14:15]
	v_pk_fma_f32 v[70:71], v[70:71], v[26:27], v[10:11]
	v_pk_fma_f32 v[68:69], v[68:69], v[24:25], v[8:9]
	v_pk_fma_f32 v[66:67], v[66:67], v[22:23], v[6:7]
	v_mov_b64_e32 v[4:5], v[36:37]
	s_cbranch_scc1 .LBB0_1349

; __device__ __forceinline__ float bf2f(bf16 b) { return __uint_as_float(((unsigned)b) << 16); }
; template <bool FULL, int DIR>
; __device__ __forceinline__ void gla_dir(const Params& p, int layer, int item, GlaSm& sm) {
;     ...
; #pragma unroll
;           for (int mi2 = 0; mi2 < 2; ++mi2)
; #pragma unroll
;             for (int e = 0; e < 16; ++e) {
;               const int i = 32 * mi2 + ROW_OF(e, hh);
;               const float ot = o[mi2][e] + bf2f(p.of[(size_t)(t0 + i) * 512 + vcol]);
.LBB0_1285:
	s_or_b64 exec, exec, s[2:3]
	s_waitcnt lgkmcnt(0)
	v_add_u32_e32 v218, 0xc1, v169
	v_ashrrev_i32_e32 v219, 31, v218
	v_lshlrev_b64 v[218:219], 10, v[218:219]
	v_lshl_add_u64 v[222:223], v[124:125], 0, v[218:219]
	global_load_ushort v176, v[222:223], off
	v_add_u32_e32 v218, 0xc2, v169
	v_ashrrev_i32_e32 v219, 31, v218
	v_lshlrev_b64 v[218:219], 10, v[218:219]
	v_lshl_add_u64 v[222:223], v[124:125], 0, v[218:219]
	global_load_ushort v177, v[222:223], off
	v_add_u32_e32 v218, 0xc3, v169
	v_ashrrev_i32_e32 v219, 31, v218
	v_lshlrev_b64 v[218:219], 10, v[218:219]
	v_lshl_add_u64 v[222:223], v[124:125], 0, v[218:219]
	global_load_ushort v178, v[222:223], off
	v_add_u32_e32 v218, 0xc8, v169
	v_ashrrev_i32_e32 v219, 31, v218
	v_lshlrev_b64 v[218:219], 10, v[218:219]
	v_lshl_add_u64 v[222:223], v[124:125], 0, v[218:219]
	global_load_ushort v179, v[222:223], off
	v_add_u32_e32 v218, 0xc9, v169
	v_ashrrev_i32_e32 v219, 31, v218
	v_lshlrev_b64 v[218:219], 10, v[218:219]
	v_lshl_add_u64 v[222:223], v[124:125], 0, v[218:219]
	global_load_ushort v180, v[222:223], off
	v_add_u32_e32 v218, 0xca, v169
	v_ashrrev_i32_e32 v219, 31, v218
	v_lshlrev_b64 v[218:219], 10, v[218:219]
	v_lshl_add_u64 v[222:223], v[124:125], 0, v[218:219]
	global_load_ushort v181, v[222:223], off
	v_add_u32_e32 v218, 0xcb, v169
	v_ashrrev_i32_e32 v219, 31, v218
	v_lshlrev_b64 v[218:219], 10, v[218:219]
	v_lshl_add_u64 v[222:223], v[124:125], 0, v[218:219]
	global_load_ushort v182, v[222:223], off
	v_add_u32_e32 v218, 0xd0, v169
	v_ashrrev_i32_e32 v219, 31, v218
	v_lshlrev_b64 v[218:219], 10, v[218:219]
	v_lshl_add_u64 v[222:223], v[124:125], 0, v[218:219]
	global_load_ushort v183, v[222:223], off
	v_add_u32_e32 v218, 0xd1, v169
	v_ashrrev_i32_e32 v219, 31, v218
	v_lshlrev_b64 v[218:219], 10, v[218:219]
	v_lshl_add_u64 v[222:223], v[124:125], 0, v[218:219]
	global_load_ushort v184, v[222:223], off
	v_add_u32_e32 v218, 0xd2, v169
	v_ashrrev_i32_e32 v219, 31, v218
	v_lshlrev_b64 v[218:219], 10, v[218:219]
	v_lshl_add_u64 v[222:223], v[124:125], 0, v[218:219]
	global_load_ushort v185, v[222:223], off
	v_add_u32_e32 v218, 0xd3, v169
	v_ashrrev_i32_e32 v219, 31, v218
	v_lshlrev_b64 v[218:219], 10, v[218:219]
	v_lshl_add_u64 v[222:223], v[124:125], 0, v[218:219]
	global_load_ushort v186, v[222:223], off
	v_add_u32_e32 v218, 0xd8, v169
	v_ashrrev_i32_e32 v219, 31, v218
	v_lshlrev_b64 v[218:219], 10, v[218:219]
	v_lshl_add_u64 v[222:223], v[124:125], 0, v[218:219]
	global_load_ushort v187, v[222:223], off
	v_add_u32_e32 v218, 0xd9, v169
	v_ashrrev_i32_e32 v219, 31, v218
	v_lshlrev_b64 v[218:219], 10, v[218:219]
	v_lshl_add_u64 v[222:223], v[124:125], 0, v[218:219]
	global_load_ushort v188, v[222:223], off
	v_add_u32_e32 v218, 0xda, v169
	v_ashrrev_i32_e32 v219, 31, v218
	v_lshlrev_b64 v[218:219], 10, v[218:219]
	v_lshl_add_u64 v[222:223], v[124:125], 0, v[218:219]
	global_load_ushort v189, v[222:223], off
	v_add_u32_e32 v218, 0xdb, v169
	v_ashrrev_i32_e32 v219, 31, v218
	v_lshlrev_b64 v[218:219], 10, v[218:219]
	v_lshl_add_u64 v[222:223], v[124:125], 0, v[218:219]
	global_load_ushort v190, v[222:223], off
	v_add_u32_e32 v218, 0xe0, v169
	v_ashrrev_i32_e32 v219, 31, v218
	v_lshlrev_b64 v[218:219], 10, v[218:219]
	v_lshl_add_u64 v[222:223], v[124:125], 0, v[218:219]
	global_load_ushort v191, v[222:223], off
	v_add_u32_e32 v218, 0xe1, v169
	v_ashrrev_i32_e32 v219, 31, v218
	v_lshlrev_b64 v[218:219], 10, v[218:219]
	v_lshl_add_u64 v[222:223], v[124:125], 0, v[218:219]
	global_load_ushort v192, v[222:223], off
	v_add_u32_e32 v218, 0xe2, v169
	v_ashrrev_i32_e32 v219, 31, v218
	v_lshlrev_b64 v[218:219], 10, v[218:219]
	v_lshl_add_u64 v[222:223], v[124:125], 0, v[218:219]
	global_load_ushort v193, v[222:223], off
	v_add_u32_e32 v218, 0xe3, v169
	v_ashrrev_i32_e32 v219, 31, v218
	v_lshlrev_b64 v[218:219], 10, v[218:219]
	v_lshl_add_u64 v[222:223], v[124:125], 0, v[218:219]
	global_load_ushort v196, v[222:223], off
	v_add_u32_e32 v218, 0xe8, v169
	v_ashrrev_i32_e32 v219, 31, v218
	v_lshlrev_b64 v[218:219], 10, v[218:219]
	v_lshl_add_u64 v[222:223], v[124:125], 0, v[218:219]
	global_load_ushort v197, v[222:223], off
	v_add_u32_e32 v218, 0xe9, v169
	v_ashrrev_i32_e32 v219, 31, v218
	v_lshlrev_b64 v[218:219], 10, v[218:219]
	v_lshl_add_u64 v[222:223], v[124:125], 0, v[218:219]
	global_load_ushort v198, v[222:223], off
	v_add_u32_e32 v218, 0xea, v169
	v_ashrrev_i32_e32 v219, 31, v218
	v_lshlrev_b64 v[218:219], 10, v[218:219]
	v_lshl_add_u64 v[222:223], v[124:125], 0, v[218:219]
	global_load_ushort v199, v[222:223], off
	v_add_u32_e32 v218, 0xeb, v169
	v_ashrrev_i32_e32 v219, 31, v218
	v_lshlrev_b64 v[218:219], 10, v[218:219]
	v_lshl_add_u64 v[222:223], v[124:125], 0, v[218:219]
	global_load_ushort v200, v[222:223], off
	v_add_u32_e32 v218, 0xf0, v169
	v_ashrrev_i32_e32 v219, 31, v218
	v_lshlrev_b64 v[218:219], 10, v[218:219]
	v_lshl_add_u64 v[222:223], v[124:125], 0, v[218:219]
	global_load_ushort v201, v[222:223], off
	v_add_u32_e32 v218, 0xf1, v169
	v_ashrrev_i32_e32 v219, 31, v218
	v_lshlrev_b64 v[218:219], 10, v[218:219]
	v_lshl_add_u64 v[222:223], v[124:125], 0, v[218:219]
	global_load_ushort v202, v[222:223], off
	v_add_u32_e32 v218, 0xf2, v169
	v_ashrrev_i32_e32 v219, 31, v218
	v_lshlrev_b64 v[218:219], 10, v[218:219]
	v_lshl_add_u64 v[222:223], v[124:125], 0, v[218:219]
	global_load_ushort v203, v[222:223], off
	v_add_u32_e32 v218, 0xf3, v169
	v_ashrrev_i32_e32 v219, 31, v218
	v_lshlrev_b64 v[218:219], 10, v[218:219]
	v_lshl_add_u64 v[222:223], v[124:125], 0, v[218:219]
	global_load_ushort v204, v[222:223], off
	v_add_u32_e32 v218, 0xf8, v169
	v_ashrrev_i32_e32 v219, 31, v218
	v_lshlrev_b64 v[218:219], 10, v[218:219]
	v_lshl_add_u64 v[222:223], v[124:125], 0, v[218:219]
	global_load_ushort v205, v[222:223], off
	v_add_u32_e32 v218, 0xf9, v169
	v_ashrrev_i32_e32 v219, 31, v218
	v_lshlrev_b64 v[218:219], 10, v[218:219]
	v_lshl_add_u64 v[222:223], v[124:125], 0, v[218:219]
	global_load_ushort v206, v[222:223], off
	v_add_u32_e32 v218, 0xfa, v169
	v_ashrrev_i32_e32 v219, 31, v218
	v_lshlrev_b64 v[218:219], 10, v[218:219]
	v_lshl_add_u64 v[222:223], v[124:125], 0, v[218:219]
	global_load_ushort v207, v[222:223], off
	v_add_u32_e32 v218, 0xfb, v169
	v_ashrrev_i32_e32 v219, 31, v218
	v_lshlrev_b64 v[218:219], 10, v[218:219]
	v_lshl_add_u64 v[222:223], v[124:125], 0, v[218:219]
	global_load_ushort v208, v[222:223], off
	s_waitcnt vmcnt(30)
; __device__ __forceinline__ float bf2f(bf16 b) { return __uint_as_float(((unsigned)b) << 16); }
; template <bool FULL, int DIR>
; __device__ __forceinline__ void gla_dir(const Params& p, int layer, int item, GlaSm& sm) {
;     ...
; #pragma unroll
;           for (int mi2 = 0; mi2 < 2; ++mi2)
; #pragma unroll
;             for (int e = 0; e < 16; ++e) {
;               const int i = 32 * mi2 + ROW_OF(e, hh);
;               const float ot = o[mi2][e] + bf2f(p.of[(size_t)(t0 + i) * 512 + vcol]);
;               o[mi2][e] = ot;
;               float ss = ot * ot;
	v_lshlrev_b32_e32 v176, 16, v176
	v_add_f32_e32 v167, v19, v176
	v_mul_f32_e32 v176, v167, v167
	s_waitcnt vmcnt(29)
	v_lshlrev_b32_e32 v177, 16, v177
	v_add_f32_e32 v166, v20, v177
	v_mul_f32_e32 v177, v166, v166
	s_waitcnt vmcnt(28)
	v_lshlrev_b32_e32 v178, 16, v178
	v_add_f32_e32 v165, v21, v178
	v_mul_f32_e32 v178, v165, v165
	s_waitcnt vmcnt(27)
	v_lshlrev_b32_e32 v179, 16, v179
	v_add_f32_e32 v164, v22, v179
	v_mul_f32_e32 v179, v164, v164
	s_waitcnt vmcnt(26)
	v_lshlrev_b32_e32 v180, 16, v180
	v_add_f32_e32 v163, v23, v180
	v_mul_f32_e32 v180, v163, v163
	s_waitcnt vmcnt(25)
	v_lshlrev_b32_e32 v181, 16, v181
	v_add_f32_e32 v162, v24, v181
	v_mul_f32_e32 v181, v162, v162
	s_waitcnt vmcnt(24)
	v_lshlrev_b32_e32 v182, 16, v182
	v_add_f32_e32 v161, v25, v182
	v_mul_f32_e32 v182, v161, v161
	s_waitcnt vmcnt(23)
	v_lshlrev_b32_e32 v183, 16, v183
	v_add_f32_e32 v160, v26, v183
	v_mul_f32_e32 v183, v160, v160
	s_waitcnt vmcnt(22)
	v_lshlrev_b32_e32 v184, 16, v184
	v_add_f32_e32 v159, v27, v184
	v_mul_f32_e32 v184, v159, v159
	s_waitcnt vmcnt(21)
	v_lshlrev_b32_e32 v185, 16, v185
	v_add_f32_e32 v158, v28, v185
	v_mul_f32_e32 v185, v158, v158
	s_waitcnt vmcnt(20)
	v_lshlrev_b32_e32 v186, 16, v186
	v_add_f32_e32 v154, v29, v186
	v_mul_f32_e32 v186, v154, v154
	s_waitcnt vmcnt(19)
	v_lshlrev_b32_e32 v187, 16, v187
	v_add_f32_e32 v153, v30, v187
	v_mul_f32_e32 v187, v153, v153
	s_waitcnt vmcnt(18)
	v_lshlrev_b32_e32 v188, 16, v188
	v_add_f32_e32 v152, v31, v188
	v_mul_f32_e32 v188, v152, v152
	s_waitcnt vmcnt(17)
	v_lshlrev_b32_e32 v189, 16, v189
	v_add_f32_e32 v151, v32, v189
	v_mul_f32_e32 v189, v151, v151
	s_waitcnt vmcnt(16)
	v_lshlrev_b32_e32 v190, 16, v190
	v_add_f32_e32 v150, v33, v190
	v_mul_f32_e32 v190, v150, v150
	s_waitcnt vmcnt(15)
	v_lshlrev_b32_e32 v191, 16, v191
	v_add_f32_e32 v149, v2, v191
	v_mul_f32_e32 v191, v149, v149
	s_waitcnt vmcnt(14)
	v_lshlrev_b32_e32 v192, 16, v192
	v_add_f32_e32 v148, v3, v192
	v_mul_f32_e32 v192, v148, v148
	s_waitcnt vmcnt(13)
	v_lshlrev_b32_e32 v193, 16, v193
	v_add_f32_e32 v147, v4, v193
	v_mul_f32_e32 v193, v147, v147
	s_waitcnt vmcnt(12)
	v_lshlrev_b32_e32 v196, 16, v196
	v_add_f32_e32 v146, v5, v196
	v_mul_f32_e32 v196, v146, v146
	s_waitcnt vmcnt(11)
	v_lshlrev_b32_e32 v197, 16, v197
	v_add_f32_e32 v145, v6, v197
	v_mul_f32_e32 v197, v145, v145
	s_waitcnt vmcnt(10)
	v_lshlrev_b32_e32 v198, 16, v198
	v_add_f32_e32 v144, v7, v198
	v_mul_f32_e32 v198, v144, v144
	s_waitcnt vmcnt(9)
	v_lshlrev_b32_e32 v199, 16, v199
	v_add_f32_e32 v143, v8, v199
	v_mul_f32_e32 v199, v143, v143
	s_waitcnt vmcnt(8)
	v_lshlrev_b32_e32 v200, 16, v200
	v_add_f32_e32 v142, v9, v200
	v_mul_f32_e32 v200, v142, v142
	s_waitcnt vmcnt(7)
	v_lshlrev_b32_e32 v201, 16, v201
	v_add_f32_e32 v141, v10, v201
	v_mul_f32_e32 v201, v141, v141
	s_waitcnt vmcnt(6)
	v_lshlrev_b32_e32 v202, 16, v202
	v_add_f32_e32 v140, v11, v202
	v_mul_f32_e32 v202, v140, v140
	s_waitcnt vmcnt(5)
	v_lshlrev_b32_e32 v203, 16, v203
	v_add_f32_e32 v139, v12, v203
	v_mul_f32_e32 v203, v139, v139
	s_waitcnt vmcnt(4)
	v_lshlrev_b32_e32 v204, 16, v204
	v_add_f32_e32 v138, v13, v204
	v_mul_f32_e32 v204, v138, v138
	s_waitcnt vmcnt(3)
	v_lshlrev_b32_e32 v205, 16, v205
	v_add_f32_e32 v137, v14, v205
	v_mul_f32_e32 v205, v137, v137
	s_waitcnt vmcnt(2)
	v_lshlrev_b32_e32 v206, 16, v206
	v_add_f32_e32 v79, v15, v206
	v_mul_f32_e32 v206, v79, v79
	s_waitcnt vmcnt(1)
	v_lshlrev_b32_e32 v207, 16, v207
	v_add_f32_e32 v16, v16, v207
	v_mul_f32_e32 v207, v16, v16
	s_waitcnt vmcnt(0)
	v_lshlrev_b32_e32 v208, 16, v208
	v_add_f32_e32 v15, v17, v208
	v_mul_f32_e32 v208, v15, v15
	v_add_u32_e32 v120, 0xc1, v169
	v_ashrrev_i32_e32 v121, 31, v120
	v_lshlrev_b64 v[120:121], 10, v[120:121]
	v_add_u32_e32 v116, 0xc2, v169
	v_ashrrev_i32_e32 v117, 31, v116
	v_lshlrev_b64 v[116:117], 10, v[116:117]
	v_add_u32_e32 v114, 0xc3, v169
	v_ashrrev_i32_e32 v115, 31, v114
	v_lshlrev_b64 v[114:115], 10, v[114:115]
	v_add_u32_e32 v112, 0xc8, v169
	v_ashrrev_i32_e32 v113, 31, v112
	v_lshlrev_b64 v[112:113], 10, v[112:113]
	v_add_u32_e32 v110, 0xc9, v169
	v_ashrrev_i32_e32 v111, 31, v110
	v_lshlrev_b64 v[110:111], 10, v[110:111]
	v_add_u32_e32 v108, 0xca, v169
	v_ashrrev_i32_e32 v109, 31, v108
	v_lshlrev_b64 v[108:109], 10, v[108:109]
	v_add_u32_e32 v106, 0xcb, v169
	v_ashrrev_i32_e32 v107, 31, v106
	v_lshlrev_b64 v[106:107], 10, v[106:107]
	v_add_u32_e32 v104, 0xd0, v169
	v_ashrrev_i32_e32 v105, 31, v104
	v_lshlrev_b64 v[104:105], 10, v[104:105]
	v_add_u32_e32 v102, 0xd1, v169
	v_ashrrev_i32_e32 v103, 31, v102
	v_lshlrev_b64 v[102:103], 10, v[102:103]
	v_add_u32_e32 v100, 0xd2, v169
	v_ashrrev_i32_e32 v101, 31, v100
	v_lshlrev_b64 v[100:101], 10, v[100:101]
	v_add_u32_e32 v98, 0xd3, v169
	v_ashrrev_i32_e32 v99, 31, v98
	v_lshlrev_b64 v[98:99], 10, v[98:99]
	v_add_u32_e32 v96, 0xd8, v169
	v_ashrrev_i32_e32 v97, 31, v96
	v_lshlrev_b64 v[96:97], 10, v[96:97]
	v_add_u32_e32 v94, 0xd9, v169
	v_ashrrev_i32_e32 v95, 31, v94
	v_lshlrev_b64 v[94:95], 10, v[94:95]
	v_add_u32_e32 v92, 0xda, v169
	v_ashrrev_i32_e32 v93, 31, v92
	v_lshlrev_b64 v[92:93], 10, v[92:93]
	v_add_u32_e32 v90, 0xdb, v169
	v_ashrrev_i32_e32 v91, 31, v90
	v_lshlrev_b64 v[90:91], 10, v[90:91]
	v_add_u32_e32 v88, 0xe0, v169
	v_ashrrev_i32_e32 v89, 31, v88
	v_lshlrev_b64 v[88:89], 10, v[88:89]
	v_add_u32_e32 v86, 0xe1, v169
	v_ashrrev_i32_e32 v87, 31, v86
	v_lshlrev_b64 v[86:87], 10, v[86:87]
	v_add_u32_e32 v84, 0xe2, v169
	v_ashrrev_i32_e32 v85, 31, v84
	v_lshlrev_b64 v[84:85], 10, v[84:85]
	v_add_u32_e32 v82, 0xe3, v169
	v_ashrrev_i32_e32 v83, 31, v82
	v_lshlrev_b64 v[82:83], 10, v[82:83]
	v_add_u32_e32 v80, 0xe8, v169
; template <bool FULL, int DIR>
; __device__ __forceinline__ void gla_dir(const Params& p, int layer, int item, GlaSm& sm) {
;     ...
;               float ss = ot * ot;
;               ss += __shfl_xor(ss, 1); ss += __shfl_xor(ss, 2); ss += __shfl_xor(ss, 4); ss += __shfl_xor(ss, 8); ss += __shfl_xor(ss, 16);
;               if (r == 0) sm.sRed[w * 64 + i] = ss;
	v_ashrrev_i32_e32 v81, 31, v80
	v_lshlrev_b64 v[80:81], 10, v[80:81]
	v_add_u32_e32 v32, 0xe9, v169
	v_ashrrev_i32_e32 v33, 31, v32
	v_lshlrev_b64 v[32:33], 10, v[32:33]
	v_add_u32_e32 v30, 0xea, v169
	v_ashrrev_i32_e32 v31, 31, v30
	v_lshlrev_b64 v[30:31], 10, v[30:31]
	v_add_u32_e32 v28, 0xeb, v169
	v_ashrrev_i32_e32 v29, 31, v28
	v_lshlrev_b64 v[28:29], 10, v[28:29]
	v_add_u32_e32 v26, 0xf0, v169
	v_ashrrev_i32_e32 v27, 31, v26
	v_lshlrev_b64 v[26:27], 10, v[26:27]
	v_add_u32_e32 v24, 0xf1, v169
	v_ashrrev_i32_e32 v25, 31, v24
	v_lshlrev_b64 v[24:25], 10, v[24:25]
	v_add_u32_e32 v22, 0xf2, v169
	v_ashrrev_i32_e32 v23, 31, v22
	v_lshlrev_b64 v[22:23], 10, v[22:23]
	v_add_u32_e32 v20, 0xf3, v169
	v_ashrrev_i32_e32 v21, 31, v20
	v_lshlrev_b64 v[20:21], 10, v[20:21]
	v_add_u32_e32 v18, 0xf8, v169
	v_ashrrev_i32_e32 v19, 31, v18
	v_lshlrev_b64 v[18:19], 10, v[18:19]
	v_add_u32_e32 v10, 0xf9, v169
	v_ashrrev_i32_e32 v11, 31, v10
	v_lshlrev_b64 v[10:11], 10, v[10:11]
	v_add_u32_e32 v8, 0xfa, v169
	v_ashrrev_i32_e32 v9, 31, v8
	v_lshlrev_b64 v[8:9], 10, v[8:9]
	v_add_u32_e32 v6, 0xfb, v169
	v_ashrrev_i32_e32 v7, 31, v6
	v_lshlrev_b64 v[6:7], 10, v[6:7]
	ds_bpermute_b32 v210, v170, v176
	ds_bpermute_b32 v211, v170, v177
	ds_bpermute_b32 v212, v170, v178
	ds_bpermute_b32 v213, v170, v179
	ds_bpermute_b32 v214, v170, v180
	ds_bpermute_b32 v215, v170, v181
	ds_bpermute_b32 v216, v170, v182
	ds_bpermute_b32 v217, v170, v183
	s_waitcnt lgkmcnt(0)
	v_fmac_f32_e32 v210, v167, v167
	v_fmac_f32_e32 v211, v166, v166
	v_fmac_f32_e32 v212, v165, v165
	v_fmac_f32_e32 v213, v164, v164
	v_fmac_f32_e32 v214, v163, v163
	v_fmac_f32_e32 v215, v162, v162
	v_fmac_f32_e32 v216, v161, v161
	v_fmac_f32_e32 v217, v160, v160
	ds_bpermute_b32 v176, v171, v210
	ds_bpermute_b32 v177, v171, v211
	ds_bpermute_b32 v178, v171, v212
	ds_bpermute_b32 v179, v171, v213
	ds_bpermute_b32 v180, v171, v214
	ds_bpermute_b32 v181, v171, v215
	ds_bpermute_b32 v182, v171, v216
	ds_bpermute_b32 v183, v171, v217
	s_waitcnt lgkmcnt(0)
	v_add_f32_e32 v210, v210, v176
	v_add_f32_e32 v211, v211, v177
	v_add_f32_e32 v212, v212, v178
	v_add_f32_e32 v213, v213, v179
	v_add_f32_e32 v214, v214, v180
	v_add_f32_e32 v215, v215, v181
	v_add_f32_e32 v216, v216, v182
	v_add_f32_e32 v217, v217, v183
	ds_bpermute_b32 v176, v172, v210
	ds_bpermute_b32 v177, v172, v211
	ds_bpermute_b32 v178, v172, v212
	ds_bpermute_b32 v179, v172, v213
	ds_bpermute_b32 v180, v172, v214
	ds_bpermute_b32 v181, v172, v215
	ds_bpermute_b32 v182, v172, v216
	ds_bpermute_b32 v183, v172, v217
	s_waitcnt lgkmcnt(0)
	v_add_f32_e32 v210, v210, v176
	v_add_f32_e32 v211, v211, v177
	v_add_f32_e32 v212, v212, v178
	v_add_f32_e32 v213, v213, v179
	v_add_f32_e32 v214, v214, v180
	v_add_f32_e32 v215, v215, v181
	v_add_f32_e32 v216, v216, v182
	v_add_f32_e32 v217, v217, v183
	ds_bpermute_b32 v176, v173, v210
	ds_bpermute_b32 v177, v173, v211
	ds_bpermute_b32 v178, v173, v212
	ds_bpermute_b32 v179, v173, v213
	ds_bpermute_b32 v180, v173, v214
	ds_bpermute_b32 v181, v173, v215
	ds_bpermute_b32 v182, v173, v216
	ds_bpermute_b32 v183, v173, v217
	s_waitcnt lgkmcnt(0)
	v_add_f32_e32 v210, v210, v176
	v_add_f32_e32 v211, v211, v177
	v_add_f32_e32 v212, v212, v178
	v_add_f32_e32 v213, v213, v179
	v_add_f32_e32 v214, v214, v180
	v_add_f32_e32 v215, v215, v181
	v_add_f32_e32 v216, v216, v182
	v_add_f32_e32 v217, v217, v183
	ds_bpermute_b32 v176, v175, v210
	ds_bpermute_b32 v177, v175, v211
	ds_bpermute_b32 v178, v175, v212
	ds_bpermute_b32 v179, v175, v213
	ds_bpermute_b32 v180, v175, v214
	ds_bpermute_b32 v181, v175, v215
	ds_bpermute_b32 v182, v175, v216
	ds_bpermute_b32 v183, v175, v217
	s_waitcnt lgkmcnt(0)
	v_add_f32_e32 v210, v210, v176
	v_add_f32_e32 v211, v211, v177
	v_add_f32_e32 v212, v212, v178
	v_add_f32_e32 v213, v213, v179
	v_add_f32_e32 v214, v214, v180
	v_add_f32_e32 v215, v215, v181
	v_add_f32_e32 v216, v216, v182
	v_add_f32_e32 v217, v217, v183
	s_and_saveexec_b64 s[2:3], vcc
	ds_write_b32 v174, v210 offset:4
	ds_write_b32 v174, v211 offset:8
	ds_write_b32 v174, v212 offset:12
	ds_write_b32 v174, v213 offset:32
	ds_write_b32 v174, v214 offset:36
	ds_write_b32 v174, v215 offset:40
	ds_write_b32 v174, v216 offset:44
	ds_write_b32 v174, v217 offset:64
	s_or_b64 exec, exec, s[2:3]
	ds_bpermute_b32 v210, v170, v184
	ds_bpermute_b32 v211, v170, v185
	ds_bpermute_b32 v212, v170, v186
	ds_bpermute_b32 v213, v170, v187
	ds_bpermute_b32 v214, v170, v188
	ds_bpermute_b32 v215, v170, v189
	ds_bpermute_b32 v216, v170, v190
	ds_bpermute_b32 v217, v170, v191
	s_waitcnt lgkmcnt(0)
	v_fmac_f32_e32 v210, v159, v159
	v_fmac_f32_e32 v211, v158, v158
	v_fmac_f32_e32 v212, v154, v154
	v_fmac_f32_e32 v213, v153, v153
	v_fmac_f32_e32 v214, v152, v152
	v_fmac_f32_e32 v215, v151, v151
	v_fmac_f32_e32 v216, v150, v150
	v_fmac_f32_e32 v217, v149, v149
	ds_bpermute_b32 v184, v171, v210
	ds_bpermute_b32 v185, v171, v211
	ds_bpermute_b32 v186, v171, v212
	ds_bpermute_b32 v187, v171, v213
	ds_bpermute_b32 v188, v171, v214
	ds_bpermute_b32 v189, v171, v215
	ds_bpermute_b32 v190, v171, v216
	ds_bpermute_b32 v191, v171, v217
	s_waitcnt lgkmcnt(0)
	v_add_f32_e32 v210, v210, v184
	v_add_f32_e32 v211, v211, v185
	v_add_f32_e32 v212, v212, v186
	v_add_f32_e32 v213, v213, v187
	v_add_f32_e32 v214, v214, v188
	v_add_f32_e32 v215, v215, v189
	v_add_f32_e32 v216, v216, v190
	v_add_f32_e32 v217, v217, v191
	ds_bpermute_b32 v184, v172, v210
	ds_bpermute_b32 v185, v172, v211
	ds_bpermute_b32 v186, v172, v212
	ds_bpermute_b32 v187, v172, v213
	ds_bpermute_b32 v188, v172, v214
	ds_bpermute_b32 v189, v172, v215
	ds_bpermute_b32 v190, v172, v216
	ds_bpermute_b32 v191, v172, v217
	s_waitcnt lgkmcnt(0)
; template <bool FULL, int DIR>
; __device__ __forceinline__ void gla_dir(const Params& p, int layer, int item, GlaSm& sm) {
;     ...
;               float ss = ot * ot;
;               ss += __shfl_xor(ss, 1); ss += __shfl_xor(ss, 2); ss += __shfl_xor(ss, 4); ss += __shfl_xor(ss, 8); ss += __shfl_xor(ss, 16);
;               if (r == 0) sm.sRed[w * 64 + i] = ss;
	v_add_f32_e32 v210, v210, v184
	v_add_f32_e32 v211, v211, v185
	v_add_f32_e32 v212, v212, v186
	v_add_f32_e32 v213, v213, v187
	v_add_f32_e32 v214, v214, v188
	v_add_f32_e32 v215, v215, v189
	v_add_f32_e32 v216, v216, v190
	v_add_f32_e32 v217, v217, v191
	ds_bpermute_b32 v184, v173, v210
	ds_bpermute_b32 v185, v173, v211
	ds_bpermute_b32 v186, v173, v212
	ds_bpermute_b32 v187, v173, v213
	ds_bpermute_b32 v188, v173, v214
	ds_bpermute_b32 v189, v173, v215
	ds_bpermute_b32 v190, v173, v216
	ds_bpermute_b32 v191, v173, v217
	s_waitcnt lgkmcnt(0)
	v_add_f32_e32 v210, v210, v184
	v_add_f32_e32 v211, v211, v185
	v_add_f32_e32 v212, v212, v186
	v_add_f32_e32 v213, v213, v187
	v_add_f32_e32 v214, v214, v188
	v_add_f32_e32 v215, v215, v189
	v_add_f32_e32 v216, v216, v190
	v_add_f32_e32 v217, v217, v191
	ds_bpermute_b32 v184, v175, v210
	ds_bpermute_b32 v185, v175, v211
	ds_bpermute_b32 v186, v175, v212
	ds_bpermute_b32 v187, v175, v213
	ds_bpermute_b32 v188, v175, v214
	ds_bpermute_b32 v189, v175, v215
	ds_bpermute_b32 v190, v175, v216
	ds_bpermute_b32 v191, v175, v217
	s_waitcnt lgkmcnt(0)
	v_add_f32_e32 v210, v210, v184
	v_add_f32_e32 v211, v211, v185
	v_add_f32_e32 v212, v212, v186
	v_add_f32_e32 v213, v213, v187
	v_add_f32_e32 v214, v214, v188
	v_add_f32_e32 v215, v215, v189
	v_add_f32_e32 v216, v216, v190
	v_add_f32_e32 v217, v217, v191
	s_and_saveexec_b64 s[2:3], vcc
	ds_write_b32 v174, v210 offset:68
	ds_write_b32 v174, v211 offset:72
	ds_write_b32 v174, v212 offset:76
	ds_write_b32 v174, v213 offset:96
	ds_write_b32 v174, v214 offset:100
	ds_write_b32 v174, v215 offset:104
	ds_write_b32 v174, v216 offset:108
	ds_write_b32 v174, v217 offset:128
	s_or_b64 exec, exec, s[2:3]
	ds_bpermute_b32 v210, v170, v192
	ds_bpermute_b32 v211, v170, v193
	ds_bpermute_b32 v212, v170, v196
	ds_bpermute_b32 v213, v170, v197
	ds_bpermute_b32 v214, v170, v198
	ds_bpermute_b32 v215, v170, v199
	ds_bpermute_b32 v216, v170, v200
	ds_bpermute_b32 v217, v170, v201
	s_waitcnt lgkmcnt(0)
	v_fmac_f32_e32 v210, v148, v148
	v_fmac_f32_e32 v211, v147, v147
	v_fmac_f32_e32 v212, v146, v146
	v_fmac_f32_e32 v213, v145, v145
	v_fmac_f32_e32 v214, v144, v144
	v_fmac_f32_e32 v215, v143, v143
	v_fmac_f32_e32 v216, v142, v142
	v_fmac_f32_e32 v217, v141, v141
	ds_bpermute_b32 v192, v171, v210
	ds_bpermute_b32 v193, v171, v211
	ds_bpermute_b32 v196, v171, v212
	ds_bpermute_b32 v197, v171, v213
	ds_bpermute_b32 v198, v171, v214
	ds_bpermute_b32 v199, v171, v215
	ds_bpermute_b32 v200, v171, v216
	ds_bpermute_b32 v201, v171, v217
	s_waitcnt lgkmcnt(0)
	v_add_f32_e32 v210, v210, v192
	v_add_f32_e32 v211, v211, v193
	v_add_f32_e32 v212, v212, v196
	v_add_f32_e32 v213, v213, v197
	v_add_f32_e32 v214, v214, v198
	v_add_f32_e32 v215, v215, v199
	v_add_f32_e32 v216, v216, v200
	v_add_f32_e32 v217, v217, v201
	ds_bpermute_b32 v192, v172, v210
	ds_bpermute_b32 v193, v172, v211
	ds_bpermute_b32 v196, v172, v212
	ds_bpermute_b32 v197, v172, v213
	ds_bpermute_b32 v198, v172, v214
	ds_bpermute_b32 v199, v172, v215
	ds_bpermute_b32 v200, v172, v216
	ds_bpermute_b32 v201, v172, v217
	s_waitcnt lgkmcnt(0)
	v_add_f32_e32 v210, v210, v192
	v_add_f32_e32 v211, v211, v193
	v_add_f32_e32 v212, v212, v196
	v_add_f32_e32 v213, v213, v197
	v_add_f32_e32 v214, v214, v198
	v_add_f32_e32 v215, v215, v199
	v_add_f32_e32 v216, v216, v200
	v_add_f32_e32 v217, v217, v201
	ds_bpermute_b32 v192, v173, v210
	ds_bpermute_b32 v193, v173, v211
	ds_bpermute_b32 v196, v173, v212
	ds_bpermute_b32 v197, v173, v213
	ds_bpermute_b32 v198, v173, v214
	ds_bpermute_b32 v199, v173, v215
	ds_bpermute_b32 v200, v173, v216
	ds_bpermute_b32 v201, v173, v217
	s_waitcnt lgkmcnt(0)
	v_add_f32_e32 v210, v210, v192
	v_add_f32_e32 v211, v211, v193
	v_add_f32_e32 v212, v212, v196
	v_add_f32_e32 v213, v213, v197
	v_add_f32_e32 v214, v214, v198
	v_add_f32_e32 v215, v215, v199
	v_add_f32_e32 v216, v216, v200
	v_add_f32_e32 v217, v217, v201
	ds_bpermute_b32 v192, v175, v210
	ds_bpermute_b32 v193, v175, v211
	ds_bpermute_b32 v196, v175, v212
	ds_bpermute_b32 v197, v175, v213
	ds_bpermute_b32 v198, v175, v214
	ds_bpermute_b32 v199, v175, v215
	ds_bpermute_b32 v200, v175, v216
	ds_bpermute_b32 v201, v175, v217
	s_waitcnt lgkmcnt(0)
; template <bool FULL, int DIR>
; __device__ __forceinline__ void gla_dir(const Params& p, int layer, int item, GlaSm& sm) {
;     ...
;               float ss = ot * ot;
;               ss += __shfl_xor(ss, 1); ss += __shfl_xor(ss, 2); ss += __shfl_xor(ss, 4); ss += __shfl_xor(ss, 8); ss += __shfl_xor(ss, 16);
;               if (r == 0) sm.sRed[w * 64 + i] = ss;
;             }
;           __syncthreads();
;           if (tid < 64) sm.sBmid[tid] = rsqrtf((sm.sRed[tid] + sm.sRed[64 + tid] + sm.sRed[128 + tid] + sm.sRed[192 + tid]) * (1.f / 128.f) + EPSF);
	v_add_f32_e32 v210, v210, v192
	v_add_f32_e32 v211, v211, v193
	v_add_f32_e32 v212, v212, v196
	v_add_f32_e32 v213, v213, v197
	v_add_f32_e32 v214, v214, v198
	v_add_f32_e32 v215, v215, v199
	v_add_f32_e32 v216, v216, v200
	v_add_f32_e32 v217, v217, v201
	s_and_saveexec_b64 s[2:3], vcc
	ds_write_b32 v174, v210 offset:132
	ds_write_b32 v174, v211 offset:136
	ds_write_b32 v174, v212 offset:140
	ds_write_b32 v174, v213 offset:160
	ds_write_b32 v174, v214 offset:164
	ds_write_b32 v174, v215 offset:168
	ds_write_b32 v174, v216 offset:172
	ds_write_b32 v174, v217 offset:192
	s_or_b64 exec, exec, s[2:3]
	ds_bpermute_b32 v210, v170, v202
	ds_bpermute_b32 v211, v170, v203
	ds_bpermute_b32 v212, v170, v204
	ds_bpermute_b32 v213, v170, v205
	ds_bpermute_b32 v214, v170, v206
	ds_bpermute_b32 v215, v170, v207
	ds_bpermute_b32 v216, v170, v208
	s_waitcnt lgkmcnt(0)
	v_fmac_f32_e32 v210, v140, v140
	v_fmac_f32_e32 v211, v139, v139
	v_fmac_f32_e32 v212, v138, v138
	v_fmac_f32_e32 v213, v137, v137
	v_fmac_f32_e32 v214, v79, v79
	v_fmac_f32_e32 v215, v16, v16
	v_fmac_f32_e32 v216, v15, v15
	ds_bpermute_b32 v202, v171, v210
	ds_bpermute_b32 v203, v171, v211
	ds_bpermute_b32 v204, v171, v212
	ds_bpermute_b32 v205, v171, v213
	ds_bpermute_b32 v206, v171, v214
	ds_bpermute_b32 v207, v171, v215
	ds_bpermute_b32 v208, v171, v216
	s_waitcnt lgkmcnt(0)
	v_add_f32_e32 v210, v210, v202
	v_add_f32_e32 v211, v211, v203
	v_add_f32_e32 v212, v212, v204
	v_add_f32_e32 v213, v213, v205
	v_add_f32_e32 v214, v214, v206
	v_add_f32_e32 v215, v215, v207
	v_add_f32_e32 v216, v216, v208
	ds_bpermute_b32 v202, v172, v210
	ds_bpermute_b32 v203, v172, v211
	ds_bpermute_b32 v204, v172, v212
	ds_bpermute_b32 v205, v172, v213
	ds_bpermute_b32 v206, v172, v214
	ds_bpermute_b32 v207, v172, v215
	ds_bpermute_b32 v208, v172, v216
	s_waitcnt lgkmcnt(0)
	v_add_f32_e32 v210, v210, v202
	v_add_f32_e32 v211, v211, v203
	v_add_f32_e32 v212, v212, v204
	v_add_f32_e32 v213, v213, v205
	v_add_f32_e32 v214, v214, v206
	v_add_f32_e32 v215, v215, v207
	v_add_f32_e32 v216, v216, v208
	ds_bpermute_b32 v202, v173, v210
	ds_bpermute_b32 v203, v173, v211
	ds_bpermute_b32 v204, v173, v212
	ds_bpermute_b32 v205, v173, v213
	ds_bpermute_b32 v206, v173, v214
	ds_bpermute_b32 v207, v173, v215
	ds_bpermute_b32 v208, v173, v216
	s_waitcnt lgkmcnt(0)
	v_add_f32_e32 v210, v210, v202
	v_add_f32_e32 v211, v211, v203
	v_add_f32_e32 v212, v212, v204
	v_add_f32_e32 v213, v213, v205
	v_add_f32_e32 v214, v214, v206
	v_add_f32_e32 v215, v215, v207
	v_add_f32_e32 v216, v216, v208
	ds_bpermute_b32 v202, v175, v210
	ds_bpermute_b32 v203, v175, v211
	ds_bpermute_b32 v204, v175, v212
	ds_bpermute_b32 v205, v175, v213
	ds_bpermute_b32 v206, v175, v214
	ds_bpermute_b32 v207, v175, v215
	ds_bpermute_b32 v208, v175, v216
	s_waitcnt lgkmcnt(0)
	v_add_f32_e32 v210, v210, v202
	v_add_f32_e32 v211, v211, v203
	v_add_f32_e32 v212, v212, v204
	v_add_f32_e32 v213, v213, v205
	v_add_f32_e32 v214, v214, v206
	v_add_f32_e32 v215, v215, v207
	v_add_f32_e32 v216, v216, v208
	s_and_saveexec_b64 s[2:3], vcc
	ds_write_b32 v174, v210 offset:196
	ds_write_b32 v174, v211 offset:200
	ds_write_b32 v174, v212 offset:204
	ds_write_b32 v174, v213 offset:224
	ds_write_b32 v174, v214 offset:228
	ds_write_b32 v174, v215 offset:232
	ds_write_b32 v174, v216 offset:236
	s_or_b64 exec, exec, s[2:3]
.LBB0_1347:
	v_cmp_gt_i32_e32 vcc, 64, v136
	s_waitcnt lgkmcnt(0)
	s_barrier
	s_and_saveexec_b64 s[2:3], vcc
	s_cbranch_execz .LBB0_1276
	v_add_u32_e32 v4, 0x11300, v135
	ds_read2st64_b32 v[2:3], v4 offset1:1
	s_waitcnt lgkmcnt(0)
	v_add_f32_e32 v5, v2, v3
	ds_read2st64_b32 v[2:3], v4 offset0:2 offset1:3
	s_waitcnt lgkmcnt(0)
	v_add_f32_e32 v2, v5, v2
	v_add_f32_e32 v2, v2, v3
	v_fmamk_f32 v2, v2, 0x3c000000, v194
	v_cmp_gt_f32_e32 vcc, s54, v2
	v_mul_f32_e32 v3, 0x4b800000, v2
	s_nop 0
	v_cndmask_b32_e32 v2, v2, v3, vcc
	v_rsq_f32_e32 v2, v2
	s_nop 0
	v_mul_f32_e32 v3, 0x45800000, v2
	v_cndmask_b32_e32 v2, v2, v3, vcc
	v_add_u32_e32 v3, 0x11000, v135
	ds_write_b32 v3, v2
	s_branch .LBB0_1276
